# peer_out: per-token H row / top-value loads software-pipelined one token ahead (plus LN3 gamma/beta preload)
# baseline (speedup 1.0000x reference)
; DI int otid() { int t = __builtin_amdgcn_workitem_id_x(); asm volatile("" : "+v"(t)); return t; }
; DI float bflo(unsigned w) { return __uint_as_float(w << 16); }
; DI float bfhi(unsigned w) { return __uint_as_float(w & 0xffff0000u); }
; DI void phase_peer_out(const Params& p, char* lds) {
;   char* ws = p.ws;
;   const int tid = otid(), lane = tid & 63, wave = tid >> 6, hb = lane >> 5, l5 = lane & 31;
;   int* sidx = (int*)lds + wave * 384; float* sw = (float*)(sidx + 128);
;   const u16* H = (const u16*)(ws + OFF_H); const unsigned* TV = (const unsigned*)(ws + OFF_TOPV);
;   const unsigned char* U6 = (const unsigned char*)(ws + OFF_U8) + 24 * l5; const unsigned char* V6 = (const unsigned char*)(ws + OFF_V8) + 24 * l5;
;   const float* USC = (const float*)(ws + OFF_USC); const float* VSC = (const float*)(ws + OFF_VSC);
;   const float* g3 = p.in[23]; const float* b3 = p.in[24];
;   int ci = 0, cj = 0; const bool cval = lane < 50;
;   if (cval) { int rem = lane, i = 0; while (true) { const int cnt = 16 / (i + 1); if (rem < cnt) break; rem -= cnt; ++i; } ci = i; cj = rem; }
;   const int flat = ci * 16 + cj;
;   for (int t = blockIdx.x * 8 + wave; t < T_TOK; t += gridDim.x * 8) {
;     f32x2 x2[16];
; #pragma unroll
;     for (int i = 0; i < 4; ++i) {
;       const uint4 hv = *(const uint4*)(H + (size_t)t * 1024 + 32 * l5 + 8 * i);
;       x2[4 * i] = f32x2{bflo(hv.x), bfhi(hv.x)}; x2[4 * i + 1] = f32x2{bflo(hv.y), bfhi(hv.y)}; x2[4 * i + 2] = f32x2{bflo(hv.z), bfhi(hv.z)}; x2[4 * i + 3] = f32x2{bflo(hv.w), bfhi(hv.w)};
;     }
;     float hval[8]; int hidx[8];
; #pragma unroll
;     for (int hq = 0; hq < 8; ++hq) {
;       const unsigned ka = TV[(size_t)t * 256 + (2 * hq) * 16 + ci], kb = TV[(size_t)t * 256 + (2 * hq + 1) * 16 + cj];
;       const float va = __uint_as_float(ka & 0xFFFFFF80u), vb = __uint_as_float(kb & 0xFFFFFF80u);
;       const int ia = 127 - (int)(ka & 127u), ib = 127 - (int)(kb & 127u);
;       hval[hq] = cval ? va + vb : -INFINITY; hidx[hq] = ia * 128 + ib;
.LBB0_1184:
	s_or_b64 exec, exec, s[2:3]
	v_ashrrev_i32_e32 v1, 6, v222
	v_readlane_b32 s0, v250, 27
	s_nop 1
	v_add_u32_e32 v60, s0, v1
	s_mov_b32 s0, 0x10000
	v_cmp_gt_i32_e64 s[0:1], s0, v60
	s_and_saveexec_b64 s[2:3], s[0:1]
	s_cbranch_execz .LBB0_1211
	s_movk_i32 s0, 0x600
	v_and_b32_e32 v5, 31, v222
	v_mul_lo_u32 v1, v1, s0
	v_readlane_b32 s0, v250, 52
	v_mul_u32_u24_e32 v2, 24, v5
	v_mov_b32_e32 v3, 0
	v_readlane_b32 s1, v250, 53
	v_add_u32_e32 v110, 0, v1
	v_lshl_add_u32 v1, v58, 4, v56
	v_lshl_add_u64 v[62:63], s[0:1], 0, v[2:3]
	v_readlane_b32 s0, v250, 54
	v_readlane_b32 s1, v250, 55
	v_sub_u32_e32 v111, 0xff, v1
	v_and_b32_e32 v1, 64, v223
	v_lshl_add_u64 v[64:65], s[0:1], 0, v[2:3]
	v_lshlrev_b32_e32 v2, 6, v5
	v_lshrrev_b32_e32 v4, 5, v0
	v_lshl_add_u64 v[66:67], s[24:25], 0, v[2:3]
	v_add_u32_e32 v7, 64, v1
	v_cmp_gt_u32_e64 s[0:1], 32, v0
	v_lshl_add_u32 v112, v0, 2, v110
	v_xor_b32_e32 v0, 32, v223
	v_readlane_b32 s16, v250, 30
	v_cmp_lt_i32_e64 s[2:3], v0, v7
	v_readlane_b32 s17, v250, 31
	v_readlane_b32 s18, v250, 32
	v_readlane_b32 s19, v250, 33
	v_cndmask_b32_e64 v0, v223, v0, s[2:3]
	v_lshlrev_b32_e32 v2, 7, v5
	v_readlane_b32 s30, v250, 44
	v_readlane_b32 s31, v250, 45
	v_readlane_b32 s16, v250, 56
	v_lshl_add_u32 v6, v5, 2, v110
	v_lshlrev_b32_e32 v8, 8, v4
	v_lshlrev_b32_e32 v113, 2, v0
	v_lshl_add_u64 v[0:1], s[30:31], 0, v[2:3]
	v_lshlrev_b32_e32 v4, 6, v4
	v_mov_b32_e32 v5, v3
	v_readlane_b32 s17, v250, 57
	v_lshl_add_u64 v[68:69], v[0:1], 0, v[4:5]
	v_readlane_b32 s18, v250, 58
	v_lshl_add_u64 v[0:1], s[16:17], 0, v[2:3]
	v_lshl_add_u64 v[70:71], v[0:1], 0, v[4:5]
	v_xor_b32_e32 v0, 8, v223
	v_cmp_lt_i32_e64 s[2:3], v0, v7
	v_readlane_b32 s19, v250, 59
	v_readlane_b32 s20, v250, 34
	v_cndmask_b32_e64 v0, v223, v0, s[2:3]
	v_lshlrev_b32_e32 v114, 2, v0
	v_xor_b32_e32 v0, 4, v223
	v_cmp_lt_i32_e64 s[2:3], v0, v7
	v_readlane_b32 s21, v250, 35
	v_readlane_b32 s22, v250, 36
	v_cndmask_b32_e64 v0, v223, v0, s[2:3]
	v_lshlrev_b32_e32 v115, 2, v0
	v_xor_b32_e32 v0, 2, v223
	v_cmp_lt_i32_e64 s[2:3], v0, v7
	v_readlane_b32 s23, v250, 37
	v_readlane_b32 s24, v250, 38
	v_cndmask_b32_e64 v0, v223, v0, s[2:3]
	v_lshlrev_b32_e32 v116, 2, v0
	v_xor_b32_e32 v0, 1, v223
	v_cmp_lt_i32_e64 s[2:3], v0, v7
	v_readlane_b32 s25, v250, 39
	v_readlane_b32 s26, v250, 40
	v_cndmask_b32_e64 v0, v223, v0, s[2:3]
	v_lshlrev_b32_e32 v117, 2, v0
	v_and_b32_e32 v0, 16, v222
	v_cmp_eq_u32_e64 s[2:3], 0, v0
	v_xor_b32_e32 v0, 16, v223
	v_cmp_lt_i32_e64 s[4:5], v0, v7
	v_readlane_b32 s27, v250, 41
	v_readlane_b32 s28, v250, 42
	v_cndmask_b32_e64 v0, v223, v0, s[4:5]
	v_lshlrev_b32_e32 v118, 2, v0
	v_and_b32_e32 v0, 8, v222
	v_cmp_eq_u32_e64 s[4:5], 0, v0
	v_and_b32_e32 v0, 4, v222
	v_cmp_eq_u32_e64 s[6:7], 0, v0
	v_and_b32_e32 v0, 2, v222
	v_cmp_eq_u32_e64 s[8:9], 0, v0
	v_and_b32_e32 v0, 1, v222
	v_readlane_b32 s29, v250, 43
	v_cmp_eq_u32_e64 s[10:11], 0, v0
	v_lshl_add_u64 v[0:1], s[18:19], 0, v[2:3]
	v_mov_b32_e32 v59, v3
	v_ashrrev_i32_e32 v57, 31, v56
	v_lshl_add_u64 v[72:73], v[0:1], 0, v[4:5]
	s_mov_b64 s[18:19], 0
	v_mov_b32_e32 v119, 0xff800000
	v_bfrev_b32_e32 v120, 1
	s_movk_i32 s21, 0xff00
	s_movk_i32 s22, 0x3fff
	s_movk_i32 s23, 0x300
	v_add_u32_e32 v121, v6, v8
	s_mov_b32 s24, 0x378e98ab
	s_mov_b32 s25, 0x3b7cd369
	s_mov_b32 s26, 0xbcc618b2
	s_mov_b32 s27, 0x3dda74e4
	s_mov_b32 s28, 0x3f228afd
	s_mov_b32 s29, 0x3e03c728
	s_mov_b32 s30, 0xbfb8aa3b
	s_mov_b32 s31, 0x42ce8ed0
	s_mov_b32 s33, 0xc2b17218
	v_mov_b32_e32 v122, 0x3ba10414
	s_brev_b32 s34, -2
	s_mov_b32 s20, 0x3f9837f0
	v_mov_b32_e32 v123, 0x3727c5ac
	s_mov_b32 s35, 0x800000
	s_mov_b32 s36, 0xffff
	v_mov_b32_e32 v124, 0xb9c68948
	v_mov_b32_e32 v125, 0x7f800000
	v_ashrrev_i32_e32 v61, 31, v60
	v_mov_b32_e32 v248, v60
	v_mov_b32_e32 v249, v61
	v_lshlrev_b64 v[36:37], 10, v[248:249]
	v_lshl_add_u64 v[36:37], s[14:15], 0, v[36:37]
	v_lshl_add_u64 v[34:35], v[56:57], 2, v[36:37]
	v_lshl_add_u64 v[32:33], v[58:59], 2, v[36:37]
	global_load_dword v231, v[34:35], off offset:64
	global_load_dword v230, v[32:33], off
	v_lshlrev_b64 v[248:249], 11, v[248:249]
	v_lshl_add_u64 v[36:37], v[66:67], 0, v[248:249]
	global_load_dwordx4 v[232:235], v[36:37], off offset:48
	global_load_dwordx4 v[236:239], v[36:37], off offset:32
	global_load_dwordx4 v[240:243], v[36:37], off offset:16
	global_load_dwordx4 v[244:247], v[36:37], off
	global_load_dword v228, v[32:33], off offset:128
	global_load_dword v226, v[32:33], off offset:256
	global_load_dword v224, v[32:33], off offset:384
	global_load_dword v222, v[32:33], off offset:512
	global_load_dword v220, v[32:33], off offset:640
	global_load_dword v218, v[32:33], off offset:768
	global_load_dword v216, v[32:33], off offset:896
	global_load_dword v229, v[34:35], off offset:192
	global_load_dword v227, v[34:35], off offset:320
	global_load_dword v225, v[34:35], off offset:448
	global_load_dword v223, v[34:35], off offset:576
	global_load_dword v221, v[34:35], off offset:704
	global_load_dword v219, v[34:35], off offset:832
	global_load_dword v217, v[34:35], off offset:960
	s_waitcnt vmcnt(0)
	global_load_dwordx4 v[184:187], v[68:69], off
	global_load_dwordx4 v[188:191], v[68:69], off offset:16
	global_load_dwordx4 v[192:195], v[68:69], off offset:32
	global_load_dwordx4 v[196:199], v[68:69], off offset:48
	global_load_dwordx4 v[200:203], v[70:71], off
	global_load_dwordx4 v[204:207], v[70:71], off offset:16
	global_load_dwordx4 v[208:211], v[70:71], off offset:32
	global_load_dwordx4 v[212:215], v[70:71], off offset:48
	s_waitcnt vmcnt(0)
	s_branch .LBB0_1187

; DI float bflo(unsigned w) { return __uint_as_float(w << 16); }
; DI float bfhi(unsigned w) { return __uint_as_float(w & 0xffff0000u); }
; DI void phase_peer_out(const Params& p, char* lds) {
;     ...
;   for (int t = blockIdx.x * 8 + wave; t < T_TOK; t += gridDim.x * 8) {
;     f32x2 x2[16];
; #pragma unroll
;     for (int i = 0; i < 4; ++i) {
;       const uint4 hv = *(const uint4*)(H + (size_t)t * 1024 + 32 * l5 + 8 * i);
;       x2[4 * i] = f32x2{bflo(hv.x), bfhi(hv.x)}; x2[4 * i + 1] = f32x2{bflo(hv.y), bfhi(hv.y)}; x2[4 * i + 2] = f32x2{bflo(hv.z), bfhi(hv.z)}; x2[4 * i + 3] = f32x2{bflo(hv.w), bfhi(hv.w)};
;     }
;     float hval[8]; int hidx[8];
; #pragma unroll
;     for (int hq = 0; hq < 8; ++hq) {
;       const unsigned ka = TV[(size_t)t * 256 + (2 * hq) * 16 + ci], kb = TV[(size_t)t * 256 + (2 * hq + 1) * 16 + cj];
;       const float va = __uint_as_float(ka & 0xFFFFFF80u), vb = __uint_as_float(kb & 0xFFFFFF80u);
;       const int ia = 127 - (int)(ka & 127u), ib = 127 - (int)(kb & 127u);
;       hval[hq] = cval ? va + vb : -INFINITY; hidx[hq] = ia * 128 + ib;
;     }
; #pragma unroll
;     for (int hq = 0; hq < 8; ++hq) {
;       const float val = hval[hq];
;       const unsigned vb32 = __float_as_uint(val);
;       const unsigned ukey = cval ? (((vb32 ^ ((vb32 >> 31) ? 0xFFFFFFFFu : 0x80000000u)) & 0xFFFFFF00u) | (unsigned)(255 - flat)) : 0u;
;       int rank = 0;
;       rank_steps10<0>(ukey, flat, rank); rank_steps10<10>(ukey, flat, rank); rank_steps10<20>(ukey, flat, rank); rank_steps10<30>(ukey, flat, rank); rank_steps10<40>(ukey, flat, rank);
.LBB0_1187:
	v_ashrrev_i32_e32 v61, 31, v60
	s_waitcnt vmcnt(4)
	v_mov_b64_e32 v[0:1], v[232:233]
	v_mov_b64_e32 v[2:3], v[234:235]
	v_mov_b64_e32 v[4:5], v[236:237]
	v_mov_b64_e32 v[6:7], v[238:239]
	v_mov_b64_e32 v[8:9], v[240:241]
	v_mov_b64_e32 v[10:11], v[242:243]
	v_mov_b64_e32 v[12:13], v[244:245]
	v_mov_b64_e32 v[14:15], v[246:247]
	v_mov_b64_e32 v[16:17], v[216:217]
	v_mov_b64_e32 v[18:19], v[218:219]
	v_mov_b64_e32 v[20:21], v[220:221]
	v_mov_b64_e32 v[22:23], v[222:223]
	v_mov_b64_e32 v[24:25], v[224:225]
	v_mov_b64_e32 v[26:27], v[226:227]
	v_mov_b64_e32 v[28:29], v[228:229]
	v_mov_b64_e32 v[30:31], v[230:231]
	v_add_u32_e32 v248, s53, v60
	v_ashrrev_i32_e32 v249, 31, v248
	v_lshlrev_b64 v[36:37], 10, v[248:249]
	v_lshl_add_u64 v[36:37], s[14:15], 0, v[36:37]
	v_lshl_add_u64 v[34:35], v[56:57], 2, v[36:37]
	v_lshl_add_u64 v[32:33], v[58:59], 2, v[36:37]
	global_load_dword v231, v[34:35], off offset:64
	global_load_dword v230, v[32:33], off
	v_lshlrev_b64 v[248:249], 11, v[248:249]
	v_lshl_add_u64 v[36:37], v[66:67], 0, v[248:249]
	global_load_dwordx4 v[232:235], v[36:37], off offset:48
	global_load_dwordx4 v[236:239], v[36:37], off offset:32
	global_load_dwordx4 v[240:243], v[36:37], off offset:16
	global_load_dwordx4 v[244:247], v[36:37], off
	global_load_dword v228, v[32:33], off offset:128
	global_load_dword v226, v[32:33], off offset:256
	global_load_dword v224, v[32:33], off offset:384
	global_load_dword v222, v[32:33], off offset:512
	global_load_dword v220, v[32:33], off offset:640
	global_load_dword v218, v[32:33], off offset:768
	global_load_dword v216, v[32:33], off offset:896
	global_load_dword v229, v[34:35], off offset:192
	global_load_dword v227, v[34:35], off offset:320
	global_load_dword v225, v[34:35], off offset:448
	global_load_dword v223, v[34:35], off offset:576
	global_load_dword v221, v[34:35], off offset:704
	global_load_dword v219, v[34:35], off offset:832
	global_load_dword v217, v[34:35], off offset:960
	v_and_b32_e32 v32, 0xffffff80, v31
	v_and_b32_e32 v33, 0xffffff80, v30
	v_add_f32_e32 v32, v32, v33
	v_cndmask_b32_e32 v33, v119, v32, vcc
	v_cmp_lt_i32_e64 s[12:13], -1, v33
	s_nop 1
	v_cndmask_b32_e64 v34, -1, v120, s[12:13]
	v_xor_b32_e32 v33, v34, v33
	v_and_or_b32 v33, v33, s21, v111
	v_cndmask_b32_e32 v33, 0, v33, vcc
	s_nop 0
	v_readlane_b32 s12, v33, 0
	v_readlane_b32 s17, v33, 2
	v_readlane_b32 s38, v33, 4
	v_cmp_gt_u32_e64 s[12:13], s12, v33
	v_readlane_b32 s40, v33, 6
	v_readlane_b32 s42, v33, 8
	v_cndmask_b32_e64 v34, 0, 1, s[12:13]
	v_cmp_gt_u32_e64 s[12:13], s17, v33
	v_readlane_b32 s44, v33, 10
	v_readlane_b32 s46, v33, 12
	v_cndmask_b32_e64 v35, 0, 1, s[12:13]
	v_cmp_gt_u32_e64 s[12:13], s38, v33
	v_readlane_b32 s48, v33, 14
	v_readlane_b32 s50, v33, 16
	v_cndmask_b32_e64 v36, 0, 1, s[12:13]
	v_cmp_gt_u32_e64 s[12:13], s40, v33
	v_readlane_b32 s52, v33, 18
	v_readlane_b32 s16, v33, 1
	v_cndmask_b32_e64 v37, 0, 1, s[12:13]
	v_cmp_gt_u32_e64 s[12:13], s42, v33
	v_readlane_b32 s37, v33, 3
	v_readlane_b32 s39, v33, 5
	v_cndmask_b32_e64 v38, 0, 1, s[12:13]
	v_cmp_gt_u32_e64 s[12:13], s44, v33
	v_readlane_b32 s41, v33, 7
	v_readlane_b32 s43, v33, 9
	v_cndmask_b32_e64 v39, 0, 1, s[12:13]
	v_cmp_gt_u32_e64 s[12:13], s46, v33
	v_readlane_b32 s45, v33, 11
	v_readlane_b32 s47, v33, 13
	v_cndmask_b32_e64 v40, 0, 1, s[12:13]
	v_cmp_gt_u32_e64 s[12:13], s48, v33
	v_readlane_b32 s49, v33, 15
	v_readlane_b32 s51, v33, 17
	v_cndmask_b32_e64 v41, 0, 1, s[12:13]
	v_cmp_gt_u32_e64 s[12:13], s50, v33
	s_nop 1
	v_cndmask_b32_e64 v42, 0, 1, s[12:13]
	v_cmp_gt_u32_e64 s[12:13], s52, v33
	s_nop 1
	v_cndmask_b32_e64 v43, 0, 1, s[12:13]
	v_cmp_gt_u32_e64 s[12:13], s16, v33
	s_nop 1
	v_addc_co_u32_e64 v34, s[12:13], 0, v34, s[12:13]
	v_cmp_gt_u32_e64 s[12:13], s37, v33
	s_nop 1
	v_addc_co_u32_e64 v34, s[12:13], v34, v35, s[12:13]
	v_cmp_gt_u32_e64 s[12:13], s39, v33
	s_nop 1
	v_addc_co_u32_e64 v34, s[12:13], v34, v36, s[12:13]
	v_cmp_gt_u32_e64 s[12:13], s41, v33
	s_nop 1
	v_addc_co_u32_e64 v34, s[12:13], v34, v37, s[12:13]
	v_cmp_gt_u32_e64 s[12:13], s43, v33
	s_nop 1
	v_addc_co_u32_e64 v34, s[12:13], v34, v38, s[12:13]
	v_cmp_gt_u32_e64 s[12:13], s45, v33
	s_nop 1
	v_addc_co_u32_e64 v34, s[12:13], v34, v39, s[12:13]
	v_cmp_gt_u32_e64 s[12:13], s47, v33
	s_nop 1
	v_addc_co_u32_e64 v34, s[12:13], v34, v40, s[12:13]
	v_cmp_gt_u32_e64 s[12:13], s49, v33
	s_nop 1
	v_addc_co_u32_e64 v34, s[12:13], v34, v41, s[12:13]
	v_cmp_gt_u32_e64 s[12:13], s51, v33
	s_nop 1
	v_addc_co_u32_e64 v34, s[12:13], v34, v42, s[12:13]
	v_readlane_b32 s12, v33, 19
	s_nop 1
	v_cmp_gt_u32_e64 s[12:13], s12, v33
	s_nop 1
	v_addc_co_u32_e64 v34, s[12:13], v34, v43, s[12:13]
	v_readlane_b32 s12, v33, 20
	s_nop 1
	v_cmp_gt_u32_e64 s[12:13], s12, v33
	s_nop 1
	v_cndmask_b32_e64 v35, 0, 1, s[12:13]
	v_readlane_b32 s12, v33, 21
	s_nop 1
	v_cmp_gt_u32_e64 s[12:13], s12, v33
	s_nop 1
	v_addc_co_u32_e64 v34, s[12:13], v34, v35, s[12:13]
	v_readlane_b32 s12, v33, 22
	s_nop 1
	v_cmp_gt_u32_e64 s[12:13], s12, v33
	s_nop 1
	v_cndmask_b32_e64 v35, 0, 1, s[12:13]
	v_readlane_b32 s12, v33, 23
	s_nop 1
	v_cmp_gt_u32_e64 s[12:13], s12, v33
	s_nop 1
	v_addc_co_u32_e64 v34, s[12:13], v34, v35, s[12:13]
	v_readlane_b32 s12, v33, 24
	s_nop 1
	v_cmp_gt_u32_e64 s[12:13], s12, v33
	s_nop 1
	v_cndmask_b32_e64 v35, 0, 1, s[12:13]
	v_readlane_b32 s12, v33, 25
	s_nop 1
	v_cmp_gt_u32_e64 s[12:13], s12, v33
	s_nop 1
	v_addc_co_u32_e64 v34, s[12:13], v34, v35, s[12:13]
	v_readlane_b32 s12, v33, 26
	s_nop 1
	v_cmp_gt_u32_e64 s[12:13], s12, v33
	s_nop 1
	v_cndmask_b32_e64 v35, 0, 1, s[12:13]
	v_readlane_b32 s12, v33, 27
	s_nop 1
	v_cmp_gt_u32_e64 s[12:13], s12, v33
	s_nop 1
; template <int C> DI void rank_step(const unsigned key, const int, int& rank) {
;   const unsigned o = (unsigned)__builtin_amdgcn_readlane((int)key, C);
;   rank += (o > key) ? 1 : 0;
; }
; DI void phase_peer_out(const Params& p, char* lds) {
;     ...
;     for (int hq = 0; hq < 8; ++hq) {
;       const float val = hval[hq];
;       const unsigned vb32 = __float_as_uint(val);
;       const unsigned ukey = cval ? (((vb32 ^ ((vb32 >> 31) ? 0xFFFFFFFFu : 0x80000000u)) & 0xFFFFFF00u) | (unsigned)(255 - flat)) : 0u;
;       int rank = 0;
;       rank_steps10<0>(ukey, flat, rank); rank_steps10<10>(ukey, flat, rank); rank_steps10<20>(ukey, flat, rank); rank_steps10<30>(ukey, flat, rank); rank_steps10<40>(ukey, flat, rank);
;       if (cval && rank < 16) { sidx[hq * 16 + rank] = hidx[hq]; sw[hq * 16 + rank] = val; }
	v_addc_co_u32_e64 v34, s[12:13], v34, v35, s[12:13]
	v_readlane_b32 s12, v33, 28
	s_nop 1
	v_cmp_gt_u32_e64 s[12:13], s12, v33
	s_nop 1
	v_cndmask_b32_e64 v35, 0, 1, s[12:13]
	v_readlane_b32 s12, v33, 29
	s_nop 1
	v_cmp_gt_u32_e64 s[12:13], s12, v33
	s_nop 1
	v_addc_co_u32_e64 v34, s[12:13], v34, v35, s[12:13]
	v_readlane_b32 s12, v33, 30
	s_nop 1
	v_cmp_gt_u32_e64 s[12:13], s12, v33
	s_nop 1
	v_cndmask_b32_e64 v35, 0, 1, s[12:13]
	v_readlane_b32 s12, v33, 31
	s_nop 1
	v_cmp_gt_u32_e64 s[12:13], s12, v33
	s_nop 1
	v_addc_co_u32_e64 v34, s[12:13], v34, v35, s[12:13]
	v_readlane_b32 s12, v33, 32
	s_nop 1
	v_cmp_gt_u32_e64 s[12:13], s12, v33
	s_nop 1
	v_cndmask_b32_e64 v35, 0, 1, s[12:13]
	v_readlane_b32 s12, v33, 33
	s_nop 1
	v_cmp_gt_u32_e64 s[12:13], s12, v33
	s_nop 1
	v_addc_co_u32_e64 v34, s[12:13], v34, v35, s[12:13]
	v_readlane_b32 s12, v33, 34
	s_nop 1
	v_cmp_gt_u32_e64 s[12:13], s12, v33
	s_nop 1
	v_cndmask_b32_e64 v35, 0, 1, s[12:13]
	v_readlane_b32 s12, v33, 35
	s_nop 1
	v_cmp_gt_u32_e64 s[12:13], s12, v33
	s_nop 1
	v_addc_co_u32_e64 v34, s[12:13], v34, v35, s[12:13]
	v_readlane_b32 s12, v33, 36
	s_nop 1
	v_cmp_gt_u32_e64 s[12:13], s12, v33
	s_nop 1
	v_cndmask_b32_e64 v35, 0, 1, s[12:13]
	v_readlane_b32 s12, v33, 37
	s_nop 1
	v_cmp_gt_u32_e64 s[12:13], s12, v33
	s_nop 1
	v_addc_co_u32_e64 v34, s[12:13], v34, v35, s[12:13]
	v_readlane_b32 s12, v33, 38
	s_nop 1
	v_cmp_gt_u32_e64 s[12:13], s12, v33
	s_nop 1
	v_cndmask_b32_e64 v35, 0, 1, s[12:13]
	v_readlane_b32 s12, v33, 39
	s_nop 1
	v_cmp_gt_u32_e64 s[12:13], s12, v33
	s_nop 1
	v_addc_co_u32_e64 v34, s[12:13], v34, v35, s[12:13]
	v_readlane_b32 s12, v33, 40
	s_nop 1
	v_cmp_gt_u32_e64 s[12:13], s12, v33
	s_nop 1
	v_cndmask_b32_e64 v35, 0, 1, s[12:13]
	v_readlane_b32 s12, v33, 41
	s_nop 1
	v_cmp_gt_u32_e64 s[12:13], s12, v33
	s_nop 1
	v_addc_co_u32_e64 v34, s[12:13], v34, v35, s[12:13]
	v_readlane_b32 s12, v33, 42
	s_nop 1
	v_cmp_gt_u32_e64 s[12:13], s12, v33
	s_nop 1
	v_cndmask_b32_e64 v35, 0, 1, s[12:13]
	v_readlane_b32 s12, v33, 43
	s_nop 1
	v_cmp_gt_u32_e64 s[12:13], s12, v33
	s_nop 1
	v_addc_co_u32_e64 v34, s[12:13], v34, v35, s[12:13]
	v_readlane_b32 s12, v33, 44
	s_nop 1
	v_cmp_gt_u32_e64 s[12:13], s12, v33
	s_nop 1
	v_cndmask_b32_e64 v35, 0, 1, s[12:13]
	v_readlane_b32 s12, v33, 45
	s_nop 1
	v_cmp_gt_u32_e64 s[12:13], s12, v33
	s_nop 1
	v_addc_co_u32_e64 v34, s[12:13], v34, v35, s[12:13]
	v_readlane_b32 s12, v33, 46
	s_nop 1
	v_cmp_gt_u32_e64 s[12:13], s12, v33
	s_nop 1
	v_cndmask_b32_e64 v35, 0, 1, s[12:13]
	v_readlane_b32 s12, v33, 47
	s_nop 1
	v_cmp_gt_u32_e64 s[12:13], s12, v33
	s_nop 1
	v_addc_co_u32_e64 v34, s[12:13], v34, v35, s[12:13]
	v_readlane_b32 s12, v33, 48
	s_nop 1
	v_cmp_gt_u32_e64 s[12:13], s12, v33
	s_nop 1
	v_cndmask_b32_e64 v35, 0, 1, s[12:13]
	v_readlane_b32 s12, v33, 49
	s_nop 1
	v_cmp_gt_u32_e64 s[12:13], s12, v33
	s_nop 1
	v_addc_co_u32_e64 v33, s[12:13], v34, v35, s[12:13]
	v_cmp_gt_u32_e64 s[12:13], 16, v33
	s_and_b64 s[16:17], vcc, s[12:13]
	s_and_saveexec_b64 s[12:13], s[16:17]
	s_cbranch_execz .LBB0_1189
	v_lshlrev_b32_e32 v30, 7, v30
	v_and_b32_e32 v31, 0x7f, v31
	v_and_b32_e32 v30, 0x3f80, v30
	v_lshl_add_u32 v33, v33, 2, v110
	v_bitop3_b32 v30, v31, s22, v30 bitop3:0x36
	ds_write2st64_b32 v33, v30, v32 offset1:2
.LBB0_1189:
	s_or_b64 exec, exec, s[12:13]
	v_and_b32_e32 v30, 0xffffff80, v28
	v_and_b32_e32 v31, 0xffffff80, v29
	v_add_f32_e32 v30, v30, v31
	v_cndmask_b32_e32 v31, v119, v30, vcc
	v_cmp_lt_i32_e64 s[12:13], -1, v31
	s_nop 1
	v_cndmask_b32_e64 v32, -1, v120, s[12:13]
	v_xor_b32_e32 v31, v32, v31
	v_and_or_b32 v31, v31, s21, v111
	v_cndmask_b32_e32 v31, 0, v31, vcc
	s_nop 0
	v_readlane_b32 s12, v31, 0
	s_nop 1
	v_cmp_gt_u32_e64 s[12:13], s12, v31
	s_nop 1
	v_cndmask_b32_e64 v32, 0, 1, s[12:13]
	v_readlane_b32 s12, v31, 1
	s_nop 1
	v_cmp_gt_u32_e64 s[12:13], s12, v31
	s_nop 1
	v_addc_co_u32_e64 v32, s[12:13], 0, v32, s[12:13]
	v_readlane_b32 s12, v31, 2
	s_nop 1
	v_cmp_gt_u32_e64 s[12:13], s12, v31
	s_nop 1
	v_cndmask_b32_e64 v33, 0, 1, s[12:13]
	v_readlane_b32 s12, v31, 3
	s_nop 1
	v_cmp_gt_u32_e64 s[12:13], s12, v31
	s_nop 1
	v_addc_co_u32_e64 v32, s[12:13], v32, v33, s[12:13]
	v_readlane_b32 s12, v31, 4
	s_nop 1
	v_cmp_gt_u32_e64 s[12:13], s12, v31
	s_nop 1
	v_cndmask_b32_e64 v33, 0, 1, s[12:13]
	v_readlane_b32 s12, v31, 5
	s_nop 1
	v_cmp_gt_u32_e64 s[12:13], s12, v31
	s_nop 1
	v_addc_co_u32_e64 v32, s[12:13], v32, v33, s[12:13]
	v_readlane_b32 s12, v31, 6
	s_nop 1
	v_cmp_gt_u32_e64 s[12:13], s12, v31
	s_nop 1
	v_cndmask_b32_e64 v33, 0, 1, s[12:13]
	v_readlane_b32 s12, v31, 7
	s_nop 1
	v_cmp_gt_u32_e64 s[12:13], s12, v31
	s_nop 1
	v_addc_co_u32_e64 v32, s[12:13], v32, v33, s[12:13]
	v_readlane_b32 s12, v31, 8
	s_nop 1
	v_cmp_gt_u32_e64 s[12:13], s12, v31
	s_nop 1
	v_cndmask_b32_e64 v33, 0, 1, s[12:13]
	v_readlane_b32 s12, v31, 9
	s_nop 1
	v_cmp_gt_u32_e64 s[12:13], s12, v31
	s_nop 1
	v_addc_co_u32_e64 v32, s[12:13], v32, v33, s[12:13]
	v_readlane_b32 s12, v31, 10
	s_nop 1
	v_cmp_gt_u32_e64 s[12:13], s12, v31
	s_nop 1
	v_cndmask_b32_e64 v33, 0, 1, s[12:13]
	v_readlane_b32 s12, v31, 11
	s_nop 1
	v_cmp_gt_u32_e64 s[12:13], s12, v31
	s_nop 1
	v_addc_co_u32_e64 v32, s[12:13], v32, v33, s[12:13]
	v_readlane_b32 s12, v31, 12
	s_nop 1
	v_cmp_gt_u32_e64 s[12:13], s12, v31
	s_nop 1
	v_cndmask_b32_e64 v33, 0, 1, s[12:13]
	v_readlane_b32 s12, v31, 13
	s_nop 1
	v_cmp_gt_u32_e64 s[12:13], s12, v31
	s_nop 1
	v_addc_co_u32_e64 v32, s[12:13], v32, v33, s[12:13]
	v_readlane_b32 s12, v31, 14
	s_nop 1
	v_cmp_gt_u32_e64 s[12:13], s12, v31
	s_nop 1
	v_cndmask_b32_e64 v33, 0, 1, s[12:13]
	v_readlane_b32 s12, v31, 15
	s_nop 1
	v_cmp_gt_u32_e64 s[12:13], s12, v31
; template <int C> DI void rank_step(const unsigned key, const int, int& rank) {
;   const unsigned o = (unsigned)__builtin_amdgcn_readlane((int)key, C);
;   rank += (o > key) ? 1 : 0;
; }
; DI void phase_peer_out(const Params& p, char* lds) {
;     ...
;     for (int hq = 0; hq < 8; ++hq) {
;       const float val = hval[hq];
;       const unsigned vb32 = __float_as_uint(val);
;       const unsigned ukey = cval ? (((vb32 ^ ((vb32 >> 31) ? 0xFFFFFFFFu : 0x80000000u)) & 0xFFFFFF00u) | (unsigned)(255 - flat)) : 0u;
;       int rank = 0;
;       rank_steps10<0>(ukey, flat, rank); rank_steps10<10>(ukey, flat, rank); rank_steps10<20>(ukey, flat, rank); rank_steps10<30>(ukey, flat, rank); rank_steps10<40>(ukey, flat, rank);
;       if (cval && rank < 16) { sidx[hq * 16 + rank] = hidx[hq]; sw[hq * 16 + rank] = val; }
	s_nop 1
	v_addc_co_u32_e64 v32, s[12:13], v32, v33, s[12:13]
	v_readlane_b32 s12, v31, 16
	s_nop 1
	v_cmp_gt_u32_e64 s[12:13], s12, v31
	s_nop 1
	v_cndmask_b32_e64 v33, 0, 1, s[12:13]
	v_readlane_b32 s12, v31, 17
	s_nop 1
	v_cmp_gt_u32_e64 s[12:13], s12, v31
	s_nop 1
	v_addc_co_u32_e64 v32, s[12:13], v32, v33, s[12:13]
	v_readlane_b32 s12, v31, 18
	s_nop 1
	v_cmp_gt_u32_e64 s[12:13], s12, v31
	s_nop 1
	v_cndmask_b32_e64 v33, 0, 1, s[12:13]
	v_readlane_b32 s12, v31, 19
	s_nop 1
	v_cmp_gt_u32_e64 s[12:13], s12, v31
	s_nop 1
	v_addc_co_u32_e64 v32, s[12:13], v32, v33, s[12:13]
	v_readlane_b32 s12, v31, 20
	s_nop 1
	v_cmp_gt_u32_e64 s[12:13], s12, v31
	s_nop 1
	v_cndmask_b32_e64 v33, 0, 1, s[12:13]
	v_readlane_b32 s12, v31, 21
	s_nop 1
	v_cmp_gt_u32_e64 s[12:13], s12, v31
	s_nop 1
	v_addc_co_u32_e64 v32, s[12:13], v32, v33, s[12:13]
	v_readlane_b32 s12, v31, 22
	s_nop 1
	v_cmp_gt_u32_e64 s[12:13], s12, v31
	s_nop 1
	v_cndmask_b32_e64 v33, 0, 1, s[12:13]
	v_readlane_b32 s12, v31, 23
	s_nop 1
	v_cmp_gt_u32_e64 s[12:13], s12, v31
	s_nop 1
	v_addc_co_u32_e64 v32, s[12:13], v32, v33, s[12:13]
	v_readlane_b32 s12, v31, 24
	s_nop 1
	v_cmp_gt_u32_e64 s[12:13], s12, v31
	s_nop 1
	v_cndmask_b32_e64 v33, 0, 1, s[12:13]
	v_readlane_b32 s12, v31, 25
	s_nop 1
	v_cmp_gt_u32_e64 s[12:13], s12, v31
	s_nop 1
	v_addc_co_u32_e64 v32, s[12:13], v32, v33, s[12:13]
	v_readlane_b32 s12, v31, 26
	s_nop 1
	v_cmp_gt_u32_e64 s[12:13], s12, v31
	s_nop 1
	v_cndmask_b32_e64 v33, 0, 1, s[12:13]
	v_readlane_b32 s12, v31, 27
	s_nop 1
	v_cmp_gt_u32_e64 s[12:13], s12, v31
	s_nop 1
	v_addc_co_u32_e64 v32, s[12:13], v32, v33, s[12:13]
	v_readlane_b32 s12, v31, 28
	s_nop 1
	v_cmp_gt_u32_e64 s[12:13], s12, v31
	s_nop 1
	v_cndmask_b32_e64 v33, 0, 1, s[12:13]
	v_readlane_b32 s12, v31, 29
	s_nop 1
	v_cmp_gt_u32_e64 s[12:13], s12, v31
	s_nop 1
	v_addc_co_u32_e64 v32, s[12:13], v32, v33, s[12:13]
	v_readlane_b32 s12, v31, 30
	s_nop 1
	v_cmp_gt_u32_e64 s[12:13], s12, v31
	s_nop 1
	v_cndmask_b32_e64 v33, 0, 1, s[12:13]
	v_readlane_b32 s12, v31, 31
	s_nop 1
	v_cmp_gt_u32_e64 s[12:13], s12, v31
	s_nop 1
	v_addc_co_u32_e64 v32, s[12:13], v32, v33, s[12:13]
	v_readlane_b32 s12, v31, 32
	s_nop 1
	v_cmp_gt_u32_e64 s[12:13], s12, v31
	s_nop 1
	v_cndmask_b32_e64 v33, 0, 1, s[12:13]
	v_readlane_b32 s12, v31, 33
	s_nop 1
	v_cmp_gt_u32_e64 s[12:13], s12, v31
	s_nop 1
	v_addc_co_u32_e64 v32, s[12:13], v32, v33, s[12:13]
	v_readlane_b32 s12, v31, 34
	s_nop 1
	v_cmp_gt_u32_e64 s[12:13], s12, v31
	s_nop 1
	v_cndmask_b32_e64 v33, 0, 1, s[12:13]
	v_readlane_b32 s12, v31, 35
	s_nop 1
	v_cmp_gt_u32_e64 s[12:13], s12, v31
	s_nop 1
	v_addc_co_u32_e64 v32, s[12:13], v32, v33, s[12:13]
	v_readlane_b32 s12, v31, 36
	s_nop 1
	v_cmp_gt_u32_e64 s[12:13], s12, v31
	s_nop 1
	v_cndmask_b32_e64 v33, 0, 1, s[12:13]
	v_readlane_b32 s12, v31, 37
	s_nop 1
	v_cmp_gt_u32_e64 s[12:13], s12, v31
	s_nop 1
	v_addc_co_u32_e64 v32, s[12:13], v32, v33, s[12:13]
	v_readlane_b32 s12, v31, 38
	s_nop 1
	v_cmp_gt_u32_e64 s[12:13], s12, v31
	s_nop 1
	v_cndmask_b32_e64 v33, 0, 1, s[12:13]
	v_readlane_b32 s12, v31, 39
	s_nop 1
	v_cmp_gt_u32_e64 s[12:13], s12, v31
	s_nop 1
	v_addc_co_u32_e64 v32, s[12:13], v32, v33, s[12:13]
	v_readlane_b32 s12, v31, 40
	s_nop 1
	v_cmp_gt_u32_e64 s[12:13], s12, v31
	s_nop 1
	v_cndmask_b32_e64 v33, 0, 1, s[12:13]
	v_readlane_b32 s12, v31, 41
	s_nop 1
	v_cmp_gt_u32_e64 s[12:13], s12, v31
	s_nop 1
	v_addc_co_u32_e64 v32, s[12:13], v32, v33, s[12:13]
	v_readlane_b32 s12, v31, 42
	s_nop 1
	v_cmp_gt_u32_e64 s[12:13], s12, v31
	s_nop 1
	v_cndmask_b32_e64 v33, 0, 1, s[12:13]
	v_readlane_b32 s12, v31, 43
	s_nop 1
	v_cmp_gt_u32_e64 s[12:13], s12, v31
	s_nop 1
	v_addc_co_u32_e64 v32, s[12:13], v32, v33, s[12:13]
	v_readlane_b32 s12, v31, 44
	s_nop 1
	v_cmp_gt_u32_e64 s[12:13], s12, v31
	s_nop 1
	v_cndmask_b32_e64 v33, 0, 1, s[12:13]
	v_readlane_b32 s12, v31, 45
	s_nop 1
	v_cmp_gt_u32_e64 s[12:13], s12, v31
	s_nop 1
	v_addc_co_u32_e64 v32, s[12:13], v32, v33, s[12:13]
	v_readlane_b32 s12, v31, 46
	s_nop 1
	v_cmp_gt_u32_e64 s[12:13], s12, v31
	s_nop 1
	v_cndmask_b32_e64 v33, 0, 1, s[12:13]
	v_readlane_b32 s12, v31, 47
	s_nop 1
	v_cmp_gt_u32_e64 s[12:13], s12, v31
	s_nop 1
	v_addc_co_u32_e64 v32, s[12:13], v32, v33, s[12:13]
	v_readlane_b32 s12, v31, 48
	s_nop 1
	v_cmp_gt_u32_e64 s[12:13], s12, v31
	s_nop 1
	v_cndmask_b32_e64 v33, 0, 1, s[12:13]
	v_readlane_b32 s12, v31, 49
	s_nop 1
	v_cmp_gt_u32_e64 s[12:13], s12, v31
	s_nop 1
	v_addc_co_u32_e64 v31, s[12:13], v32, v33, s[12:13]
	v_cmp_gt_u32_e64 s[12:13], 16, v31
	s_and_b64 s[16:17], vcc, s[12:13]
	s_and_saveexec_b64 s[12:13], s[16:17]
	s_cbranch_execz .LBB0_1191
	v_lshlrev_b32_e32 v28, 7, v28
	v_and_b32_e32 v29, 0x7f, v29
	v_and_b32_e32 v28, 0x3f80, v28
	v_bitop3_b32 v28, v29, s22, v28 bitop3:0x36
	v_lshl_add_u32 v29, v31, 2, v110
	ds_write2_b32 v29, v28, v30 offset0:16 offset1:144
; template <int C> DI void rank_step(const unsigned key, const int, int& rank) {
;   const unsigned o = (unsigned)__builtin_amdgcn_readlane((int)key, C);
;   rank += (o > key) ? 1 : 0;
; }
; DI void phase_peer_out(const Params& p, char* lds) {
;     ...
;     for (int hq = 0; hq < 8; ++hq) {
;       const float val = hval[hq];
;       const unsigned vb32 = __float_as_uint(val);
;       const unsigned ukey = cval ? (((vb32 ^ ((vb32 >> 31) ? 0xFFFFFFFFu : 0x80000000u)) & 0xFFFFFF00u) | (unsigned)(255 - flat)) : 0u;
;       int rank = 0;
;       rank_steps10<0>(ukey, flat, rank); rank_steps10<10>(ukey, flat, rank); rank_steps10<20>(ukey, flat, rank); rank_steps10<30>(ukey, flat, rank); rank_steps10<40>(ukey, flat, rank);
;       if (cval && rank < 16) { sidx[hq * 16 + rank] = hidx[hq]; sw[hq * 16 + rank] = val; }
.LBB0_1191:
	s_or_b64 exec, exec, s[12:13]
	v_and_b32_e32 v28, 0xffffff80, v26
	v_and_b32_e32 v29, 0xffffff80, v27
	v_add_f32_e32 v28, v28, v29
	v_cndmask_b32_e32 v29, v119, v28, vcc
	v_cmp_lt_i32_e64 s[12:13], -1, v29
	s_nop 1
	v_cndmask_b32_e64 v30, -1, v120, s[12:13]
	v_xor_b32_e32 v29, v30, v29
	v_and_or_b32 v29, v29, s21, v111
	v_cndmask_b32_e32 v29, 0, v29, vcc
	s_nop 0
	v_readlane_b32 s12, v29, 0
	s_nop 1
	v_cmp_gt_u32_e64 s[12:13], s12, v29
	s_nop 1
	v_cndmask_b32_e64 v30, 0, 1, s[12:13]
	v_readlane_b32 s12, v29, 1
	s_nop 1
	v_cmp_gt_u32_e64 s[12:13], s12, v29
	s_nop 1
	v_addc_co_u32_e64 v30, s[12:13], 0, v30, s[12:13]
	v_readlane_b32 s12, v29, 2
	s_nop 1
	v_cmp_gt_u32_e64 s[12:13], s12, v29
	s_nop 1
	v_cndmask_b32_e64 v31, 0, 1, s[12:13]
	v_readlane_b32 s12, v29, 3
	s_nop 1
	v_cmp_gt_u32_e64 s[12:13], s12, v29
	s_nop 1
	v_addc_co_u32_e64 v30, s[12:13], v30, v31, s[12:13]
	v_readlane_b32 s12, v29, 4
	s_nop 1
	v_cmp_gt_u32_e64 s[12:13], s12, v29
	s_nop 1
	v_cndmask_b32_e64 v31, 0, 1, s[12:13]
	v_readlane_b32 s12, v29, 5
	s_nop 1
	v_cmp_gt_u32_e64 s[12:13], s12, v29
	s_nop 1
	v_addc_co_u32_e64 v30, s[12:13], v30, v31, s[12:13]
	v_readlane_b32 s12, v29, 6
	s_nop 1
	v_cmp_gt_u32_e64 s[12:13], s12, v29
	s_nop 1
	v_cndmask_b32_e64 v31, 0, 1, s[12:13]
	v_readlane_b32 s12, v29, 7
	s_nop 1
	v_cmp_gt_u32_e64 s[12:13], s12, v29
	s_nop 1
	v_addc_co_u32_e64 v30, s[12:13], v30, v31, s[12:13]
	v_readlane_b32 s12, v29, 8
	s_nop 1
	v_cmp_gt_u32_e64 s[12:13], s12, v29
	s_nop 1
	v_cndmask_b32_e64 v31, 0, 1, s[12:13]
	v_readlane_b32 s12, v29, 9
	s_nop 1
	v_cmp_gt_u32_e64 s[12:13], s12, v29
	s_nop 1
	v_addc_co_u32_e64 v30, s[12:13], v30, v31, s[12:13]
	v_readlane_b32 s12, v29, 10
	s_nop 1
	v_cmp_gt_u32_e64 s[12:13], s12, v29
	s_nop 1
	v_cndmask_b32_e64 v31, 0, 1, s[12:13]
	v_readlane_b32 s12, v29, 11
	s_nop 1
	v_cmp_gt_u32_e64 s[12:13], s12, v29
	s_nop 1
	v_addc_co_u32_e64 v30, s[12:13], v30, v31, s[12:13]
	v_readlane_b32 s12, v29, 12
	s_nop 1
	v_cmp_gt_u32_e64 s[12:13], s12, v29
	s_nop 1
	v_cndmask_b32_e64 v31, 0, 1, s[12:13]
	v_readlane_b32 s12, v29, 13
	s_nop 1
	v_cmp_gt_u32_e64 s[12:13], s12, v29
	s_nop 1
	v_addc_co_u32_e64 v30, s[12:13], v30, v31, s[12:13]
	v_readlane_b32 s12, v29, 14
	s_nop 1
	v_cmp_gt_u32_e64 s[12:13], s12, v29
	s_nop 1
	v_cndmask_b32_e64 v31, 0, 1, s[12:13]
	v_readlane_b32 s12, v29, 15
	s_nop 1
	v_cmp_gt_u32_e64 s[12:13], s12, v29
	s_nop 1
	v_addc_co_u32_e64 v30, s[12:13], v30, v31, s[12:13]
	v_readlane_b32 s12, v29, 16
	s_nop 1
	v_cmp_gt_u32_e64 s[12:13], s12, v29
	s_nop 1
	v_cndmask_b32_e64 v31, 0, 1, s[12:13]
	v_readlane_b32 s12, v29, 17
	s_nop 1
	v_cmp_gt_u32_e64 s[12:13], s12, v29
	s_nop 1
	v_addc_co_u32_e64 v30, s[12:13], v30, v31, s[12:13]
	v_readlane_b32 s12, v29, 18
	s_nop 1
	v_cmp_gt_u32_e64 s[12:13], s12, v29
	s_nop 1
	v_cndmask_b32_e64 v31, 0, 1, s[12:13]
	v_readlane_b32 s12, v29, 19
	s_nop 1
	v_cmp_gt_u32_e64 s[12:13], s12, v29
	s_nop 1
	v_addc_co_u32_e64 v30, s[12:13], v30, v31, s[12:13]
	v_readlane_b32 s12, v29, 20
	s_nop 1
	v_cmp_gt_u32_e64 s[12:13], s12, v29
	s_nop 1
	v_cndmask_b32_e64 v31, 0, 1, s[12:13]
	v_readlane_b32 s12, v29, 21
	s_nop 1
	v_cmp_gt_u32_e64 s[12:13], s12, v29
	s_nop 1
	v_addc_co_u32_e64 v30, s[12:13], v30, v31, s[12:13]
	v_readlane_b32 s12, v29, 22
	s_nop 1
	v_cmp_gt_u32_e64 s[12:13], s12, v29
	s_nop 1
	v_cndmask_b32_e64 v31, 0, 1, s[12:13]
	v_readlane_b32 s12, v29, 23
	s_nop 1
	v_cmp_gt_u32_e64 s[12:13], s12, v29
	s_nop 1
	v_addc_co_u32_e64 v30, s[12:13], v30, v31, s[12:13]
	v_readlane_b32 s12, v29, 24
	s_nop 1
	v_cmp_gt_u32_e64 s[12:13], s12, v29
	s_nop 1
	v_cndmask_b32_e64 v31, 0, 1, s[12:13]
	v_readlane_b32 s12, v29, 25
	s_nop 1
	v_cmp_gt_u32_e64 s[12:13], s12, v29
	s_nop 1
	v_addc_co_u32_e64 v30, s[12:13], v30, v31, s[12:13]
	v_readlane_b32 s12, v29, 26
	s_nop 1
	v_cmp_gt_u32_e64 s[12:13], s12, v29
	s_nop 1
	v_cndmask_b32_e64 v31, 0, 1, s[12:13]
	v_readlane_b32 s12, v29, 27
	s_nop 1
	v_cmp_gt_u32_e64 s[12:13], s12, v29
	s_nop 1
	v_addc_co_u32_e64 v30, s[12:13], v30, v31, s[12:13]
	v_readlane_b32 s12, v29, 28
	s_nop 1
	v_cmp_gt_u32_e64 s[12:13], s12, v29
	s_nop 1
	v_cndmask_b32_e64 v31, 0, 1, s[12:13]
	v_readlane_b32 s12, v29, 29
	s_nop 1
	v_cmp_gt_u32_e64 s[12:13], s12, v29
	s_nop 1
	v_addc_co_u32_e64 v30, s[12:13], v30, v31, s[12:13]
	v_readlane_b32 s12, v29, 30
	s_nop 1
	v_cmp_gt_u32_e64 s[12:13], s12, v29
	s_nop 1
	v_cndmask_b32_e64 v31, 0, 1, s[12:13]
	v_readlane_b32 s12, v29, 31
	s_nop 1
	v_cmp_gt_u32_e64 s[12:13], s12, v29
	s_nop 1
	v_addc_co_u32_e64 v30, s[12:13], v30, v31, s[12:13]
	v_readlane_b32 s12, v29, 32
	s_nop 1
	v_cmp_gt_u32_e64 s[12:13], s12, v29
	s_nop 1
	v_cndmask_b32_e64 v31, 0, 1, s[12:13]
	v_readlane_b32 s12, v29, 33
	s_nop 1
	v_cmp_gt_u32_e64 s[12:13], s12, v29
	s_nop 1
	v_addc_co_u32_e64 v30, s[12:13], v30, v31, s[12:13]
	v_readlane_b32 s12, v29, 34
	s_nop 1
	v_cmp_gt_u32_e64 s[12:13], s12, v29
	s_nop 1
	v_cndmask_b32_e64 v31, 0, 1, s[12:13]
	v_readlane_b32 s12, v29, 35
	s_nop 1
	v_cmp_gt_u32_e64 s[12:13], s12, v29
	s_nop 1
	v_addc_co_u32_e64 v30, s[12:13], v30, v31, s[12:13]
	v_readlane_b32 s12, v29, 36
	s_nop 1
	v_cmp_gt_u32_e64 s[12:13], s12, v29
	s_nop 1
	v_cndmask_b32_e64 v31, 0, 1, s[12:13]
	v_readlane_b32 s12, v29, 37
	s_nop 1
	v_cmp_gt_u32_e64 s[12:13], s12, v29
	s_nop 1
	v_addc_co_u32_e64 v30, s[12:13], v30, v31, s[12:13]
	v_readlane_b32 s12, v29, 38
	s_nop 1
	v_cmp_gt_u32_e64 s[12:13], s12, v29
	s_nop 1
	v_cndmask_b32_e64 v31, 0, 1, s[12:13]
	v_readlane_b32 s12, v29, 39
	s_nop 1
	v_cmp_gt_u32_e64 s[12:13], s12, v29
	s_nop 1
	v_addc_co_u32_e64 v30, s[12:13], v30, v31, s[12:13]
	v_readlane_b32 s12, v29, 40
	s_nop 1
	v_cmp_gt_u32_e64 s[12:13], s12, v29
	s_nop 1
	v_cndmask_b32_e64 v31, 0, 1, s[12:13]
	v_readlane_b32 s12, v29, 41
	s_nop 1
	v_cmp_gt_u32_e64 s[12:13], s12, v29
	s_nop 1
	v_addc_co_u32_e64 v30, s[12:13], v30, v31, s[12:13]
	v_readlane_b32 s12, v29, 42
	s_nop 1
	v_cmp_gt_u32_e64 s[12:13], s12, v29
	s_nop 1
	v_cndmask_b32_e64 v31, 0, 1, s[12:13]
	v_readlane_b32 s12, v29, 43
	s_nop 1
	v_cmp_gt_u32_e64 s[12:13], s12, v29
	s_nop 1
	v_addc_co_u32_e64 v30, s[12:13], v30, v31, s[12:13]
	v_readlane_b32 s12, v29, 44
	s_nop 1
	v_cmp_gt_u32_e64 s[12:13], s12, v29
	s_nop 1
	v_cndmask_b32_e64 v31, 0, 1, s[12:13]
	v_readlane_b32 s12, v29, 45
	s_nop 1
	v_cmp_gt_u32_e64 s[12:13], s12, v29
	s_nop 1
	v_addc_co_u32_e64 v30, s[12:13], v30, v31, s[12:13]
	v_readlane_b32 s12, v29, 46
	s_nop 1
	v_cmp_gt_u32_e64 s[12:13], s12, v29
	s_nop 1
	v_cndmask_b32_e64 v31, 0, 1, s[12:13]
	v_readlane_b32 s12, v29, 47
	s_nop 1
	v_cmp_gt_u32_e64 s[12:13], s12, v29
	s_nop 1
	v_addc_co_u32_e64 v30, s[12:13], v30, v31, s[12:13]
	v_readlane_b32 s12, v29, 48
	s_nop 1
	v_cmp_gt_u32_e64 s[12:13], s12, v29
	s_nop 1
	v_cndmask_b32_e64 v31, 0, 1, s[12:13]
	v_readlane_b32 s12, v29, 49
	s_nop 1
	v_cmp_gt_u32_e64 s[12:13], s12, v29
	s_nop 1
	v_addc_co_u32_e64 v29, s[12:13], v30, v31, s[12:13]
	v_cmp_gt_u32_e64 s[12:13], 16, v29
	s_and_b64 s[16:17], vcc, s[12:13]
	s_and_saveexec_b64 s[12:13], s[16:17]
	s_cbranch_execz .LBB0_1193
; template <int C> DI void rank_step(const unsigned key, const int, int& rank) {
;   const unsigned o = (unsigned)__builtin_amdgcn_readlane((int)key, C);
;   rank += (o > key) ? 1 : 0;
; }
; DI void phase_peer_out(const Params& p, char* lds) {
;     ...
;     for (int hq = 0; hq < 8; ++hq) {
;       const float val = hval[hq];
;       const unsigned vb32 = __float_as_uint(val);
;       const unsigned ukey = cval ? (((vb32 ^ ((vb32 >> 31) ? 0xFFFFFFFFu : 0x80000000u)) & 0xFFFFFF00u) | (unsigned)(255 - flat)) : 0u;
;       int rank = 0;
;       rank_steps10<0>(ukey, flat, rank); rank_steps10<10>(ukey, flat, rank); rank_steps10<20>(ukey, flat, rank); rank_steps10<30>(ukey, flat, rank); rank_steps10<40>(ukey, flat, rank);
;       if (cval && rank < 16) { sidx[hq * 16 + rank] = hidx[hq]; sw[hq * 16 + rank] = val; }
	v_lshlrev_b32_e32 v26, 7, v26
	v_and_b32_e32 v27, 0x7f, v27
	v_and_b32_e32 v26, 0x3f80, v26
	v_bitop3_b32 v26, v27, s22, v26 bitop3:0x36
	v_lshl_add_u32 v27, v29, 2, v110
	ds_write2_b32 v27, v26, v28 offset0:32 offset1:160
.LBB0_1193:
	s_or_b64 exec, exec, s[12:13]
	v_and_b32_e32 v26, 0xffffff80, v24
	v_and_b32_e32 v27, 0xffffff80, v25
	v_add_f32_e32 v26, v26, v27
	v_cndmask_b32_e32 v27, v119, v26, vcc
	v_cmp_lt_i32_e64 s[12:13], -1, v27
	s_nop 1
	v_cndmask_b32_e64 v28, -1, v120, s[12:13]
	v_xor_b32_e32 v27, v28, v27
	v_and_or_b32 v27, v27, s21, v111
	v_cndmask_b32_e32 v27, 0, v27, vcc
	s_nop 0
	v_readlane_b32 s12, v27, 0
	s_nop 1
	v_cmp_gt_u32_e64 s[12:13], s12, v27
	s_nop 1
	v_cndmask_b32_e64 v28, 0, 1, s[12:13]
	v_readlane_b32 s12, v27, 1
	s_nop 1
	v_cmp_gt_u32_e64 s[12:13], s12, v27
	s_nop 1
	v_addc_co_u32_e64 v28, s[12:13], 0, v28, s[12:13]
	v_readlane_b32 s12, v27, 2
	s_nop 1
	v_cmp_gt_u32_e64 s[12:13], s12, v27
	s_nop 1
	v_cndmask_b32_e64 v29, 0, 1, s[12:13]
	v_readlane_b32 s12, v27, 3
	s_nop 1
	v_cmp_gt_u32_e64 s[12:13], s12, v27
	s_nop 1
	v_addc_co_u32_e64 v28, s[12:13], v28, v29, s[12:13]
	v_readlane_b32 s12, v27, 4
	s_nop 1
	v_cmp_gt_u32_e64 s[12:13], s12, v27
	s_nop 1
	v_cndmask_b32_e64 v29, 0, 1, s[12:13]
	v_readlane_b32 s12, v27, 5
	s_nop 1
	v_cmp_gt_u32_e64 s[12:13], s12, v27
	s_nop 1
	v_addc_co_u32_e64 v28, s[12:13], v28, v29, s[12:13]
	v_readlane_b32 s12, v27, 6
	s_nop 1
	v_cmp_gt_u32_e64 s[12:13], s12, v27
	s_nop 1
	v_cndmask_b32_e64 v29, 0, 1, s[12:13]
	v_readlane_b32 s12, v27, 7
	s_nop 1
	v_cmp_gt_u32_e64 s[12:13], s12, v27
	s_nop 1
	v_addc_co_u32_e64 v28, s[12:13], v28, v29, s[12:13]
	v_readlane_b32 s12, v27, 8
	s_nop 1
	v_cmp_gt_u32_e64 s[12:13], s12, v27
	s_nop 1
	v_cndmask_b32_e64 v29, 0, 1, s[12:13]
	v_readlane_b32 s12, v27, 9
	s_nop 1
	v_cmp_gt_u32_e64 s[12:13], s12, v27
	s_nop 1
	v_addc_co_u32_e64 v28, s[12:13], v28, v29, s[12:13]
	v_readlane_b32 s12, v27, 10
	s_nop 1
	v_cmp_gt_u32_e64 s[12:13], s12, v27
	s_nop 1
	v_cndmask_b32_e64 v29, 0, 1, s[12:13]
	v_readlane_b32 s12, v27, 11
	s_nop 1
	v_cmp_gt_u32_e64 s[12:13], s12, v27
	s_nop 1
	v_addc_co_u32_e64 v28, s[12:13], v28, v29, s[12:13]
	v_readlane_b32 s12, v27, 12
	s_nop 1
	v_cmp_gt_u32_e64 s[12:13], s12, v27
	s_nop 1
	v_cndmask_b32_e64 v29, 0, 1, s[12:13]
	v_readlane_b32 s12, v27, 13
	s_nop 1
	v_cmp_gt_u32_e64 s[12:13], s12, v27
	s_nop 1
	v_addc_co_u32_e64 v28, s[12:13], v28, v29, s[12:13]
	v_readlane_b32 s12, v27, 14
	s_nop 1
	v_cmp_gt_u32_e64 s[12:13], s12, v27
	s_nop 1
	v_cndmask_b32_e64 v29, 0, 1, s[12:13]
	v_readlane_b32 s12, v27, 15
	s_nop 1
	v_cmp_gt_u32_e64 s[12:13], s12, v27
	s_nop 1
	v_addc_co_u32_e64 v28, s[12:13], v28, v29, s[12:13]
	v_readlane_b32 s12, v27, 16
	s_nop 1
	v_cmp_gt_u32_e64 s[12:13], s12, v27
	s_nop 1
	v_cndmask_b32_e64 v29, 0, 1, s[12:13]
	v_readlane_b32 s12, v27, 17
	s_nop 1
	v_cmp_gt_u32_e64 s[12:13], s12, v27
	s_nop 1
	v_addc_co_u32_e64 v28, s[12:13], v28, v29, s[12:13]
	v_readlane_b32 s12, v27, 18
	s_nop 1
	v_cmp_gt_u32_e64 s[12:13], s12, v27
	s_nop 1
	v_cndmask_b32_e64 v29, 0, 1, s[12:13]
	v_readlane_b32 s12, v27, 19
	s_nop 1
	v_cmp_gt_u32_e64 s[12:13], s12, v27
	s_nop 1
	v_addc_co_u32_e64 v28, s[12:13], v28, v29, s[12:13]
	v_readlane_b32 s12, v27, 20
	s_nop 1
	v_cmp_gt_u32_e64 s[12:13], s12, v27
	s_nop 1
	v_cndmask_b32_e64 v29, 0, 1, s[12:13]
	v_readlane_b32 s12, v27, 21
	s_nop 1
	v_cmp_gt_u32_e64 s[12:13], s12, v27
	s_nop 1
	v_addc_co_u32_e64 v28, s[12:13], v28, v29, s[12:13]
	v_readlane_b32 s12, v27, 22
	s_nop 1
	v_cmp_gt_u32_e64 s[12:13], s12, v27
	s_nop 1
	v_cndmask_b32_e64 v29, 0, 1, s[12:13]
	v_readlane_b32 s12, v27, 23
	s_nop 1
	v_cmp_gt_u32_e64 s[12:13], s12, v27
	s_nop 1
	v_addc_co_u32_e64 v28, s[12:13], v28, v29, s[12:13]
	v_readlane_b32 s12, v27, 24
	s_nop 1
	v_cmp_gt_u32_e64 s[12:13], s12, v27
	s_nop 1
	v_cndmask_b32_e64 v29, 0, 1, s[12:13]
	v_readlane_b32 s12, v27, 25
	s_nop 1
	v_cmp_gt_u32_e64 s[12:13], s12, v27
	s_nop 1
	v_addc_co_u32_e64 v28, s[12:13], v28, v29, s[12:13]
	v_readlane_b32 s12, v27, 26
	s_nop 1
	v_cmp_gt_u32_e64 s[12:13], s12, v27
	s_nop 1
	v_cndmask_b32_e64 v29, 0, 1, s[12:13]
	v_readlane_b32 s12, v27, 27
	s_nop 1
	v_cmp_gt_u32_e64 s[12:13], s12, v27
	s_nop 1
	v_addc_co_u32_e64 v28, s[12:13], v28, v29, s[12:13]
	v_readlane_b32 s12, v27, 28
	s_nop 1
	v_cmp_gt_u32_e64 s[12:13], s12, v27
	s_nop 1
	v_cndmask_b32_e64 v29, 0, 1, s[12:13]
	v_readlane_b32 s12, v27, 29
	s_nop 1
	v_cmp_gt_u32_e64 s[12:13], s12, v27
	s_nop 1
	v_addc_co_u32_e64 v28, s[12:13], v28, v29, s[12:13]
	v_readlane_b32 s12, v27, 30
	s_nop 1
	v_cmp_gt_u32_e64 s[12:13], s12, v27
	s_nop 1
	v_cndmask_b32_e64 v29, 0, 1, s[12:13]
	v_readlane_b32 s12, v27, 31
	s_nop 1
	v_cmp_gt_u32_e64 s[12:13], s12, v27
	s_nop 1
	v_addc_co_u32_e64 v28, s[12:13], v28, v29, s[12:13]
	v_readlane_b32 s12, v27, 32
	s_nop 1
	v_cmp_gt_u32_e64 s[12:13], s12, v27
	s_nop 1
	v_cndmask_b32_e64 v29, 0, 1, s[12:13]
	v_readlane_b32 s12, v27, 33
	s_nop 1
	v_cmp_gt_u32_e64 s[12:13], s12, v27
	s_nop 1
	v_addc_co_u32_e64 v28, s[12:13], v28, v29, s[12:13]
	v_readlane_b32 s12, v27, 34
	s_nop 1
	v_cmp_gt_u32_e64 s[12:13], s12, v27
	s_nop 1
	v_cndmask_b32_e64 v29, 0, 1, s[12:13]
	v_readlane_b32 s12, v27, 35
	s_nop 1
	v_cmp_gt_u32_e64 s[12:13], s12, v27
	s_nop 1
	v_addc_co_u32_e64 v28, s[12:13], v28, v29, s[12:13]
	v_readlane_b32 s12, v27, 36
	s_nop 1
	v_cmp_gt_u32_e64 s[12:13], s12, v27
	s_nop 1
	v_cndmask_b32_e64 v29, 0, 1, s[12:13]
	v_readlane_b32 s12, v27, 37
	s_nop 1
	v_cmp_gt_u32_e64 s[12:13], s12, v27
	s_nop 1
	v_addc_co_u32_e64 v28, s[12:13], v28, v29, s[12:13]
	v_readlane_b32 s12, v27, 38
	s_nop 1
	v_cmp_gt_u32_e64 s[12:13], s12, v27
	s_nop 1
	v_cndmask_b32_e64 v29, 0, 1, s[12:13]
; template <int C> DI void rank_step(const unsigned key, const int, int& rank) {
;   const unsigned o = (unsigned)__builtin_amdgcn_readlane((int)key, C);
;   rank += (o > key) ? 1 : 0;
; }
; DI void phase_peer_out(const Params& p, char* lds) {
;     ...
;     for (int hq = 0; hq < 8; ++hq) {
;       const float val = hval[hq];
;       const unsigned vb32 = __float_as_uint(val);
;       const unsigned ukey = cval ? (((vb32 ^ ((vb32 >> 31) ? 0xFFFFFFFFu : 0x80000000u)) & 0xFFFFFF00u) | (unsigned)(255 - flat)) : 0u;
;       int rank = 0;
;       rank_steps10<0>(ukey, flat, rank); rank_steps10<10>(ukey, flat, rank); rank_steps10<20>(ukey, flat, rank); rank_steps10<30>(ukey, flat, rank); rank_steps10<40>(ukey, flat, rank);
;       if (cval && rank < 16) { sidx[hq * 16 + rank] = hidx[hq]; sw[hq * 16 + rank] = val; }
	v_readlane_b32 s12, v27, 39
	s_nop 1
	v_cmp_gt_u32_e64 s[12:13], s12, v27
	s_nop 1
	v_addc_co_u32_e64 v28, s[12:13], v28, v29, s[12:13]
	v_readlane_b32 s12, v27, 40
	s_nop 1
	v_cmp_gt_u32_e64 s[12:13], s12, v27
	s_nop 1
	v_cndmask_b32_e64 v29, 0, 1, s[12:13]
	v_readlane_b32 s12, v27, 41
	s_nop 1
	v_cmp_gt_u32_e64 s[12:13], s12, v27
	s_nop 1
	v_addc_co_u32_e64 v28, s[12:13], v28, v29, s[12:13]
	v_readlane_b32 s12, v27, 42
	s_nop 1
	v_cmp_gt_u32_e64 s[12:13], s12, v27
	s_nop 1
	v_cndmask_b32_e64 v29, 0, 1, s[12:13]
	v_readlane_b32 s12, v27, 43
	s_nop 1
	v_cmp_gt_u32_e64 s[12:13], s12, v27
	s_nop 1
	v_addc_co_u32_e64 v28, s[12:13], v28, v29, s[12:13]
	v_readlane_b32 s12, v27, 44
	s_nop 1
	v_cmp_gt_u32_e64 s[12:13], s12, v27
	s_nop 1
	v_cndmask_b32_e64 v29, 0, 1, s[12:13]
	v_readlane_b32 s12, v27, 45
	s_nop 1
	v_cmp_gt_u32_e64 s[12:13], s12, v27
	s_nop 1
	v_addc_co_u32_e64 v28, s[12:13], v28, v29, s[12:13]
	v_readlane_b32 s12, v27, 46
	s_nop 1
	v_cmp_gt_u32_e64 s[12:13], s12, v27
	s_nop 1
	v_cndmask_b32_e64 v29, 0, 1, s[12:13]
	v_readlane_b32 s12, v27, 47
	s_nop 1
	v_cmp_gt_u32_e64 s[12:13], s12, v27
	s_nop 1
	v_addc_co_u32_e64 v28, s[12:13], v28, v29, s[12:13]
	v_readlane_b32 s12, v27, 48
	s_nop 1
	v_cmp_gt_u32_e64 s[12:13], s12, v27
	s_nop 1
	v_cndmask_b32_e64 v29, 0, 1, s[12:13]
	v_readlane_b32 s12, v27, 49
	s_nop 1
	v_cmp_gt_u32_e64 s[12:13], s12, v27
	s_nop 1
	v_addc_co_u32_e64 v27, s[12:13], v28, v29, s[12:13]
	v_cmp_gt_u32_e64 s[12:13], 16, v27
	s_and_b64 s[16:17], vcc, s[12:13]
	s_and_saveexec_b64 s[12:13], s[16:17]
	s_cbranch_execz .LBB0_1195
	v_lshlrev_b32_e32 v24, 7, v24
	v_and_b32_e32 v25, 0x7f, v25
	v_and_b32_e32 v24, 0x3f80, v24
	v_bitop3_b32 v24, v25, s22, v24 bitop3:0x36
	v_lshl_add_u32 v25, v27, 2, v110
	ds_write2_b32 v25, v24, v26 offset0:48 offset1:176
.LBB0_1195:
	s_or_b64 exec, exec, s[12:13]
	v_and_b32_e32 v24, 0xffffff80, v22
	v_and_b32_e32 v25, 0xffffff80, v23
	v_add_f32_e32 v24, v24, v25
	v_cndmask_b32_e32 v25, v119, v24, vcc
	v_cmp_lt_i32_e64 s[12:13], -1, v25
	s_nop 1
	v_cndmask_b32_e64 v26, -1, v120, s[12:13]
	v_xor_b32_e32 v25, v26, v25
	v_and_or_b32 v25, v25, s21, v111
	v_cndmask_b32_e32 v25, 0, v25, vcc
	s_nop 0
	v_readlane_b32 s12, v25, 0
	s_nop 1
	v_cmp_gt_u32_e64 s[12:13], s12, v25
	s_nop 1
	v_cndmask_b32_e64 v26, 0, 1, s[12:13]
	v_readlane_b32 s12, v25, 1
	s_nop 1
	v_cmp_gt_u32_e64 s[12:13], s12, v25
	s_nop 1
	v_addc_co_u32_e64 v26, s[12:13], 0, v26, s[12:13]
	v_readlane_b32 s12, v25, 2
	s_nop 1
	v_cmp_gt_u32_e64 s[12:13], s12, v25
	s_nop 1
	v_cndmask_b32_e64 v27, 0, 1, s[12:13]
	v_readlane_b32 s12, v25, 3
	s_nop 1
	v_cmp_gt_u32_e64 s[12:13], s12, v25
	s_nop 1
	v_addc_co_u32_e64 v26, s[12:13], v26, v27, s[12:13]
	v_readlane_b32 s12, v25, 4
	s_nop 1
	v_cmp_gt_u32_e64 s[12:13], s12, v25
	s_nop 1
	v_cndmask_b32_e64 v27, 0, 1, s[12:13]
	v_readlane_b32 s12, v25, 5
	s_nop 1
	v_cmp_gt_u32_e64 s[12:13], s12, v25
	s_nop 1
	v_addc_co_u32_e64 v26, s[12:13], v26, v27, s[12:13]
	v_readlane_b32 s12, v25, 6
	s_nop 1
	v_cmp_gt_u32_e64 s[12:13], s12, v25
	s_nop 1
	v_cndmask_b32_e64 v27, 0, 1, s[12:13]
	v_readlane_b32 s12, v25, 7
	s_nop 1
	v_cmp_gt_u32_e64 s[12:13], s12, v25
	s_nop 1
	v_addc_co_u32_e64 v26, s[12:13], v26, v27, s[12:13]
	v_readlane_b32 s12, v25, 8
	s_nop 1
	v_cmp_gt_u32_e64 s[12:13], s12, v25
	s_nop 1
	v_cndmask_b32_e64 v27, 0, 1, s[12:13]
	v_readlane_b32 s12, v25, 9
	s_nop 1
	v_cmp_gt_u32_e64 s[12:13], s12, v25
	s_nop 1
	v_addc_co_u32_e64 v26, s[12:13], v26, v27, s[12:13]
	v_readlane_b32 s12, v25, 10
	s_nop 1
	v_cmp_gt_u32_e64 s[12:13], s12, v25
	s_nop 1
	v_cndmask_b32_e64 v27, 0, 1, s[12:13]
	v_readlane_b32 s12, v25, 11
	s_nop 1
	v_cmp_gt_u32_e64 s[12:13], s12, v25
	s_nop 1
	v_addc_co_u32_e64 v26, s[12:13], v26, v27, s[12:13]
	v_readlane_b32 s12, v25, 12
	s_nop 1
	v_cmp_gt_u32_e64 s[12:13], s12, v25
	s_nop 1
	v_cndmask_b32_e64 v27, 0, 1, s[12:13]
	v_readlane_b32 s12, v25, 13
	s_nop 1
	v_cmp_gt_u32_e64 s[12:13], s12, v25
	s_nop 1
	v_addc_co_u32_e64 v26, s[12:13], v26, v27, s[12:13]
	v_readlane_b32 s12, v25, 14
	s_nop 1
	v_cmp_gt_u32_e64 s[12:13], s12, v25
	s_nop 1
	v_cndmask_b32_e64 v27, 0, 1, s[12:13]
	v_readlane_b32 s12, v25, 15
	s_nop 1
	v_cmp_gt_u32_e64 s[12:13], s12, v25
	s_nop 1
	v_addc_co_u32_e64 v26, s[12:13], v26, v27, s[12:13]
	v_readlane_b32 s12, v25, 16
	s_nop 1
	v_cmp_gt_u32_e64 s[12:13], s12, v25
	s_nop 1
	v_cndmask_b32_e64 v27, 0, 1, s[12:13]
	v_readlane_b32 s12, v25, 17
	s_nop 1
	v_cmp_gt_u32_e64 s[12:13], s12, v25
	s_nop 1
	v_addc_co_u32_e64 v26, s[12:13], v26, v27, s[12:13]
	v_readlane_b32 s12, v25, 18
	s_nop 1
	v_cmp_gt_u32_e64 s[12:13], s12, v25
	s_nop 1
	v_cndmask_b32_e64 v27, 0, 1, s[12:13]
	v_readlane_b32 s12, v25, 19
	s_nop 1
	v_cmp_gt_u32_e64 s[12:13], s12, v25
	s_nop 1
	v_addc_co_u32_e64 v26, s[12:13], v26, v27, s[12:13]
	v_readlane_b32 s12, v25, 20
	s_nop 1
	v_cmp_gt_u32_e64 s[12:13], s12, v25
	s_nop 1
	v_cndmask_b32_e64 v27, 0, 1, s[12:13]
	v_readlane_b32 s12, v25, 21
	s_nop 1
	v_cmp_gt_u32_e64 s[12:13], s12, v25
	s_nop 1
	v_addc_co_u32_e64 v26, s[12:13], v26, v27, s[12:13]
	v_readlane_b32 s12, v25, 22
	s_nop 1
	v_cmp_gt_u32_e64 s[12:13], s12, v25
	s_nop 1
	v_cndmask_b32_e64 v27, 0, 1, s[12:13]
	v_readlane_b32 s12, v25, 23
	s_nop 1
	v_cmp_gt_u32_e64 s[12:13], s12, v25
	s_nop 1
	v_addc_co_u32_e64 v26, s[12:13], v26, v27, s[12:13]
	v_readlane_b32 s12, v25, 24
	s_nop 1
	v_cmp_gt_u32_e64 s[12:13], s12, v25
	s_nop 1
	v_cndmask_b32_e64 v27, 0, 1, s[12:13]
	v_readlane_b32 s12, v25, 25
	s_nop 1
	v_cmp_gt_u32_e64 s[12:13], s12, v25
	s_nop 1
	v_addc_co_u32_e64 v26, s[12:13], v26, v27, s[12:13]
	v_readlane_b32 s12, v25, 26
	s_nop 1
	v_cmp_gt_u32_e64 s[12:13], s12, v25
	s_nop 1
; template <int C> DI void rank_step(const unsigned key, const int, int& rank) {
;   const unsigned o = (unsigned)__builtin_amdgcn_readlane((int)key, C);
;   rank += (o > key) ? 1 : 0;
; }
; DI void phase_peer_out(const Params& p, char* lds) {
;     ...
;     for (int hq = 0; hq < 8; ++hq) {
;       const float val = hval[hq];
;       const unsigned vb32 = __float_as_uint(val);
;       const unsigned ukey = cval ? (((vb32 ^ ((vb32 >> 31) ? 0xFFFFFFFFu : 0x80000000u)) & 0xFFFFFF00u) | (unsigned)(255 - flat)) : 0u;
;       int rank = 0;
;       rank_steps10<0>(ukey, flat, rank); rank_steps10<10>(ukey, flat, rank); rank_steps10<20>(ukey, flat, rank); rank_steps10<30>(ukey, flat, rank); rank_steps10<40>(ukey, flat, rank);
;       if (cval && rank < 16) { sidx[hq * 16 + rank] = hidx[hq]; sw[hq * 16 + rank] = val; }
	v_cndmask_b32_e64 v27, 0, 1, s[12:13]
	v_readlane_b32 s12, v25, 27
	s_nop 1
	v_cmp_gt_u32_e64 s[12:13], s12, v25
	s_nop 1
	v_addc_co_u32_e64 v26, s[12:13], v26, v27, s[12:13]
	v_readlane_b32 s12, v25, 28
	s_nop 1
	v_cmp_gt_u32_e64 s[12:13], s12, v25
	s_nop 1
	v_cndmask_b32_e64 v27, 0, 1, s[12:13]
	v_readlane_b32 s12, v25, 29
	s_nop 1
	v_cmp_gt_u32_e64 s[12:13], s12, v25
	s_nop 1
	v_addc_co_u32_e64 v26, s[12:13], v26, v27, s[12:13]
	v_readlane_b32 s12, v25, 30
	s_nop 1
	v_cmp_gt_u32_e64 s[12:13], s12, v25
	s_nop 1
	v_cndmask_b32_e64 v27, 0, 1, s[12:13]
	v_readlane_b32 s12, v25, 31
	s_nop 1
	v_cmp_gt_u32_e64 s[12:13], s12, v25
	s_nop 1
	v_addc_co_u32_e64 v26, s[12:13], v26, v27, s[12:13]
	v_readlane_b32 s12, v25, 32
	s_nop 1
	v_cmp_gt_u32_e64 s[12:13], s12, v25
	s_nop 1
	v_cndmask_b32_e64 v27, 0, 1, s[12:13]
	v_readlane_b32 s12, v25, 33
	s_nop 1
	v_cmp_gt_u32_e64 s[12:13], s12, v25
	s_nop 1
	v_addc_co_u32_e64 v26, s[12:13], v26, v27, s[12:13]
	v_readlane_b32 s12, v25, 34
	s_nop 1
	v_cmp_gt_u32_e64 s[12:13], s12, v25
	s_nop 1
	v_cndmask_b32_e64 v27, 0, 1, s[12:13]
	v_readlane_b32 s12, v25, 35
	s_nop 1
	v_cmp_gt_u32_e64 s[12:13], s12, v25
	s_nop 1
	v_addc_co_u32_e64 v26, s[12:13], v26, v27, s[12:13]
	v_readlane_b32 s12, v25, 36
	s_nop 1
	v_cmp_gt_u32_e64 s[12:13], s12, v25
	s_nop 1
	v_cndmask_b32_e64 v27, 0, 1, s[12:13]
	v_readlane_b32 s12, v25, 37
	s_nop 1
	v_cmp_gt_u32_e64 s[12:13], s12, v25
	s_nop 1
	v_addc_co_u32_e64 v26, s[12:13], v26, v27, s[12:13]
	v_readlane_b32 s12, v25, 38
	s_nop 1
	v_cmp_gt_u32_e64 s[12:13], s12, v25
	s_nop 1
	v_cndmask_b32_e64 v27, 0, 1, s[12:13]
	v_readlane_b32 s12, v25, 39
	s_nop 1
	v_cmp_gt_u32_e64 s[12:13], s12, v25
	s_nop 1
	v_addc_co_u32_e64 v26, s[12:13], v26, v27, s[12:13]
	v_readlane_b32 s12, v25, 40
	s_nop 1
	v_cmp_gt_u32_e64 s[12:13], s12, v25
	s_nop 1
	v_cndmask_b32_e64 v27, 0, 1, s[12:13]
	v_readlane_b32 s12, v25, 41
	s_nop 1
	v_cmp_gt_u32_e64 s[12:13], s12, v25
	s_nop 1
	v_addc_co_u32_e64 v26, s[12:13], v26, v27, s[12:13]
	v_readlane_b32 s12, v25, 42
	s_nop 1
	v_cmp_gt_u32_e64 s[12:13], s12, v25
	s_nop 1
	v_cndmask_b32_e64 v27, 0, 1, s[12:13]
	v_readlane_b32 s12, v25, 43
	s_nop 1
	v_cmp_gt_u32_e64 s[12:13], s12, v25
	s_nop 1
	v_addc_co_u32_e64 v26, s[12:13], v26, v27, s[12:13]
	v_readlane_b32 s12, v25, 44
	s_nop 1
	v_cmp_gt_u32_e64 s[12:13], s12, v25
	s_nop 1
	v_cndmask_b32_e64 v27, 0, 1, s[12:13]
	v_readlane_b32 s12, v25, 45
	s_nop 1
	v_cmp_gt_u32_e64 s[12:13], s12, v25
	s_nop 1
	v_addc_co_u32_e64 v26, s[12:13], v26, v27, s[12:13]
	v_readlane_b32 s12, v25, 46
	s_nop 1
	v_cmp_gt_u32_e64 s[12:13], s12, v25
	s_nop 1
	v_cndmask_b32_e64 v27, 0, 1, s[12:13]
	v_readlane_b32 s12, v25, 47
	s_nop 1
	v_cmp_gt_u32_e64 s[12:13], s12, v25
	s_nop 1
	v_addc_co_u32_e64 v26, s[12:13], v26, v27, s[12:13]
	v_readlane_b32 s12, v25, 48
	s_nop 1
	v_cmp_gt_u32_e64 s[12:13], s12, v25
	s_nop 1
	v_cndmask_b32_e64 v27, 0, 1, s[12:13]
	v_readlane_b32 s12, v25, 49
	s_nop 1
	v_cmp_gt_u32_e64 s[12:13], s12, v25
	s_nop 1
	v_addc_co_u32_e64 v25, s[12:13], v26, v27, s[12:13]
	v_cmp_gt_u32_e64 s[12:13], 16, v25
	s_and_b64 s[16:17], vcc, s[12:13]
	s_and_saveexec_b64 s[12:13], s[16:17]
	s_cbranch_execz .LBB0_1197
	v_lshlrev_b32_e32 v22, 7, v22
	v_and_b32_e32 v23, 0x7f, v23
	v_and_b32_e32 v22, 0x3f80, v22
	v_bitop3_b32 v22, v23, s22, v22 bitop3:0x36
	v_lshl_add_u32 v23, v25, 2, v110
	ds_write2st64_b32 v23, v22, v24 offset0:1 offset1:3
.LBB0_1197:
	s_or_b64 exec, exec, s[12:13]
	v_and_b32_e32 v22, 0xffffff80, v20
	v_and_b32_e32 v23, 0xffffff80, v21
	v_add_f32_e32 v22, v22, v23
	v_cndmask_b32_e32 v23, v119, v22, vcc
	v_cmp_lt_i32_e64 s[12:13], -1, v23
	s_nop 1
	v_cndmask_b32_e64 v24, -1, v120, s[12:13]
	v_xor_b32_e32 v23, v24, v23
	v_and_or_b32 v23, v23, s21, v111
	v_cndmask_b32_e32 v23, 0, v23, vcc
	s_nop 0
	v_readlane_b32 s12, v23, 0
	s_nop 1
	v_cmp_gt_u32_e64 s[12:13], s12, v23
	s_nop 1
	v_cndmask_b32_e64 v24, 0, 1, s[12:13]
	v_readlane_b32 s12, v23, 1
	s_nop 1
	v_cmp_gt_u32_e64 s[12:13], s12, v23
	s_nop 1
	v_addc_co_u32_e64 v24, s[12:13], 0, v24, s[12:13]
	v_readlane_b32 s12, v23, 2
	s_nop 1
	v_cmp_gt_u32_e64 s[12:13], s12, v23
	s_nop 1
	v_cndmask_b32_e64 v25, 0, 1, s[12:13]
	v_readlane_b32 s12, v23, 3
	s_nop 1
	v_cmp_gt_u32_e64 s[12:13], s12, v23
	s_nop 1
	v_addc_co_u32_e64 v24, s[12:13], v24, v25, s[12:13]
	v_readlane_b32 s12, v23, 4
	s_nop 1
	v_cmp_gt_u32_e64 s[12:13], s12, v23
	s_nop 1
	v_cndmask_b32_e64 v25, 0, 1, s[12:13]
	v_readlane_b32 s12, v23, 5
	s_nop 1
	v_cmp_gt_u32_e64 s[12:13], s12, v23
	s_nop 1
	v_addc_co_u32_e64 v24, s[12:13], v24, v25, s[12:13]
	v_readlane_b32 s12, v23, 6
	s_nop 1
	v_cmp_gt_u32_e64 s[12:13], s12, v23
	s_nop 1
	v_cndmask_b32_e64 v25, 0, 1, s[12:13]
	v_readlane_b32 s12, v23, 7
	s_nop 1
	v_cmp_gt_u32_e64 s[12:13], s12, v23
	s_nop 1
	v_addc_co_u32_e64 v24, s[12:13], v24, v25, s[12:13]
	v_readlane_b32 s12, v23, 8
	s_nop 1
	v_cmp_gt_u32_e64 s[12:13], s12, v23
	s_nop 1
	v_cndmask_b32_e64 v25, 0, 1, s[12:13]
	v_readlane_b32 s12, v23, 9
	s_nop 1
	v_cmp_gt_u32_e64 s[12:13], s12, v23
	s_nop 1
	v_addc_co_u32_e64 v24, s[12:13], v24, v25, s[12:13]
	v_readlane_b32 s12, v23, 10
	s_nop 1
	v_cmp_gt_u32_e64 s[12:13], s12, v23
	s_nop 1
	v_cndmask_b32_e64 v25, 0, 1, s[12:13]
	v_readlane_b32 s12, v23, 11
	s_nop 1
	v_cmp_gt_u32_e64 s[12:13], s12, v23
	s_nop 1
	v_addc_co_u32_e64 v24, s[12:13], v24, v25, s[12:13]
	v_readlane_b32 s12, v23, 12
	s_nop 1
	v_cmp_gt_u32_e64 s[12:13], s12, v23
	s_nop 1
	v_cndmask_b32_e64 v25, 0, 1, s[12:13]
	v_readlane_b32 s12, v23, 13
	s_nop 1
	v_cmp_gt_u32_e64 s[12:13], s12, v23
	s_nop 1
	v_addc_co_u32_e64 v24, s[12:13], v24, v25, s[12:13]
	v_readlane_b32 s12, v23, 14
	s_nop 1
; template <int C> DI void rank_step(const unsigned key, const int, int& rank) {
;   const unsigned o = (unsigned)__builtin_amdgcn_readlane((int)key, C);
;   rank += (o > key) ? 1 : 0;
; }
; DI void phase_peer_out(const Params& p, char* lds) {
;     ...
;     for (int hq = 0; hq < 8; ++hq) {
;       const float val = hval[hq];
;       const unsigned vb32 = __float_as_uint(val);
;       const unsigned ukey = cval ? (((vb32 ^ ((vb32 >> 31) ? 0xFFFFFFFFu : 0x80000000u)) & 0xFFFFFF00u) | (unsigned)(255 - flat)) : 0u;
;       int rank = 0;
;       rank_steps10<0>(ukey, flat, rank); rank_steps10<10>(ukey, flat, rank); rank_steps10<20>(ukey, flat, rank); rank_steps10<30>(ukey, flat, rank); rank_steps10<40>(ukey, flat, rank);
;       if (cval && rank < 16) { sidx[hq * 16 + rank] = hidx[hq]; sw[hq * 16 + rank] = val; }
	v_cmp_gt_u32_e64 s[12:13], s12, v23
	s_nop 1
	v_cndmask_b32_e64 v25, 0, 1, s[12:13]
	v_readlane_b32 s12, v23, 15
	s_nop 1
	v_cmp_gt_u32_e64 s[12:13], s12, v23
	s_nop 1
	v_addc_co_u32_e64 v24, s[12:13], v24, v25, s[12:13]
	v_readlane_b32 s12, v23, 16
	s_nop 1
	v_cmp_gt_u32_e64 s[12:13], s12, v23
	s_nop 1
	v_cndmask_b32_e64 v25, 0, 1, s[12:13]
	v_readlane_b32 s12, v23, 17
	s_nop 1
	v_cmp_gt_u32_e64 s[12:13], s12, v23
	s_nop 1
	v_addc_co_u32_e64 v24, s[12:13], v24, v25, s[12:13]
	v_readlane_b32 s12, v23, 18
	s_nop 1
	v_cmp_gt_u32_e64 s[12:13], s12, v23
	s_nop 1
	v_cndmask_b32_e64 v25, 0, 1, s[12:13]
	v_readlane_b32 s12, v23, 19
	s_nop 1
	v_cmp_gt_u32_e64 s[12:13], s12, v23
	s_nop 1
	v_addc_co_u32_e64 v24, s[12:13], v24, v25, s[12:13]
	v_readlane_b32 s12, v23, 20
	s_nop 1
	v_cmp_gt_u32_e64 s[12:13], s12, v23
	s_nop 1
	v_cndmask_b32_e64 v25, 0, 1, s[12:13]
	v_readlane_b32 s12, v23, 21
	s_nop 1
	v_cmp_gt_u32_e64 s[12:13], s12, v23
	s_nop 1
	v_addc_co_u32_e64 v24, s[12:13], v24, v25, s[12:13]
	v_readlane_b32 s12, v23, 22
	s_nop 1
	v_cmp_gt_u32_e64 s[12:13], s12, v23
	s_nop 1
	v_cndmask_b32_e64 v25, 0, 1, s[12:13]
	v_readlane_b32 s12, v23, 23
	s_nop 1
	v_cmp_gt_u32_e64 s[12:13], s12, v23
	s_nop 1
	v_addc_co_u32_e64 v24, s[12:13], v24, v25, s[12:13]
	v_readlane_b32 s12, v23, 24
	s_nop 1
	v_cmp_gt_u32_e64 s[12:13], s12, v23
	s_nop 1
	v_cndmask_b32_e64 v25, 0, 1, s[12:13]
	v_readlane_b32 s12, v23, 25
	s_nop 1
	v_cmp_gt_u32_e64 s[12:13], s12, v23
	s_nop 1
	v_addc_co_u32_e64 v24, s[12:13], v24, v25, s[12:13]
	v_readlane_b32 s12, v23, 26
	s_nop 1
	v_cmp_gt_u32_e64 s[12:13], s12, v23
	s_nop 1
	v_cndmask_b32_e64 v25, 0, 1, s[12:13]
	v_readlane_b32 s12, v23, 27
	s_nop 1
	v_cmp_gt_u32_e64 s[12:13], s12, v23
	s_nop 1
	v_addc_co_u32_e64 v24, s[12:13], v24, v25, s[12:13]
	v_readlane_b32 s12, v23, 28
	s_nop 1
	v_cmp_gt_u32_e64 s[12:13], s12, v23
	s_nop 1
	v_cndmask_b32_e64 v25, 0, 1, s[12:13]
	v_readlane_b32 s12, v23, 29
	s_nop 1
	v_cmp_gt_u32_e64 s[12:13], s12, v23
	s_nop 1
	v_addc_co_u32_e64 v24, s[12:13], v24, v25, s[12:13]
	v_readlane_b32 s12, v23, 30
	s_nop 1
	v_cmp_gt_u32_e64 s[12:13], s12, v23
	s_nop 1
	v_cndmask_b32_e64 v25, 0, 1, s[12:13]
	v_readlane_b32 s12, v23, 31
	s_nop 1
	v_cmp_gt_u32_e64 s[12:13], s12, v23
	s_nop 1
	v_addc_co_u32_e64 v24, s[12:13], v24, v25, s[12:13]
	v_readlane_b32 s12, v23, 32
	s_nop 1
	v_cmp_gt_u32_e64 s[12:13], s12, v23
	s_nop 1
	v_cndmask_b32_e64 v25, 0, 1, s[12:13]
	v_readlane_b32 s12, v23, 33
	s_nop 1
	v_cmp_gt_u32_e64 s[12:13], s12, v23
	s_nop 1
	v_addc_co_u32_e64 v24, s[12:13], v24, v25, s[12:13]
	v_readlane_b32 s12, v23, 34
	s_nop 1
	v_cmp_gt_u32_e64 s[12:13], s12, v23
	s_nop 1
	v_cndmask_b32_e64 v25, 0, 1, s[12:13]
	v_readlane_b32 s12, v23, 35
	s_nop 1
	v_cmp_gt_u32_e64 s[12:13], s12, v23
	s_nop 1
	v_addc_co_u32_e64 v24, s[12:13], v24, v25, s[12:13]
	v_readlane_b32 s12, v23, 36
	s_nop 1
	v_cmp_gt_u32_e64 s[12:13], s12, v23
	s_nop 1
	v_cndmask_b32_e64 v25, 0, 1, s[12:13]
	v_readlane_b32 s12, v23, 37
	s_nop 1
	v_cmp_gt_u32_e64 s[12:13], s12, v23
	s_nop 1
	v_addc_co_u32_e64 v24, s[12:13], v24, v25, s[12:13]
	v_readlane_b32 s12, v23, 38
	s_nop 1
	v_cmp_gt_u32_e64 s[12:13], s12, v23
	s_nop 1
	v_cndmask_b32_e64 v25, 0, 1, s[12:13]
	v_readlane_b32 s12, v23, 39
	s_nop 1
	v_cmp_gt_u32_e64 s[12:13], s12, v23
	s_nop 1
	v_addc_co_u32_e64 v24, s[12:13], v24, v25, s[12:13]
	v_readlane_b32 s12, v23, 40
	s_nop 1
	v_cmp_gt_u32_e64 s[12:13], s12, v23
	s_nop 1
	v_cndmask_b32_e64 v25, 0, 1, s[12:13]
	v_readlane_b32 s12, v23, 41
	s_nop 1
	v_cmp_gt_u32_e64 s[12:13], s12, v23
	s_nop 1
	v_addc_co_u32_e64 v24, s[12:13], v24, v25, s[12:13]
	v_readlane_b32 s12, v23, 42
	s_nop 1
	v_cmp_gt_u32_e64 s[12:13], s12, v23
	s_nop 1
	v_cndmask_b32_e64 v25, 0, 1, s[12:13]
	v_readlane_b32 s12, v23, 43
	s_nop 1
	v_cmp_gt_u32_e64 s[12:13], s12, v23
	s_nop 1
	v_addc_co_u32_e64 v24, s[12:13], v24, v25, s[12:13]
	v_readlane_b32 s12, v23, 44
	s_nop 1
	v_cmp_gt_u32_e64 s[12:13], s12, v23
	s_nop 1
	v_cndmask_b32_e64 v25, 0, 1, s[12:13]
	v_readlane_b32 s12, v23, 45
	s_nop 1
	v_cmp_gt_u32_e64 s[12:13], s12, v23
	s_nop 1
	v_addc_co_u32_e64 v24, s[12:13], v24, v25, s[12:13]
	v_readlane_b32 s12, v23, 46
	s_nop 1
	v_cmp_gt_u32_e64 s[12:13], s12, v23
	s_nop 1
	v_cndmask_b32_e64 v25, 0, 1, s[12:13]
	v_readlane_b32 s12, v23, 47
	s_nop 1
	v_cmp_gt_u32_e64 s[12:13], s12, v23
	s_nop 1
	v_addc_co_u32_e64 v24, s[12:13], v24, v25, s[12:13]
	v_readlane_b32 s12, v23, 48
	s_nop 1
	v_cmp_gt_u32_e64 s[12:13], s12, v23
	s_nop 1
	v_cndmask_b32_e64 v25, 0, 1, s[12:13]
	v_readlane_b32 s12, v23, 49
	s_nop 1
	v_cmp_gt_u32_e64 s[12:13], s12, v23
	s_nop 1
	v_addc_co_u32_e64 v23, s[12:13], v24, v25, s[12:13]
	v_cmp_gt_u32_e64 s[12:13], 16, v23
	s_and_b64 s[16:17], vcc, s[12:13]
	s_and_saveexec_b64 s[12:13], s[16:17]
	s_cbranch_execz .LBB0_1199
	v_lshlrev_b32_e32 v20, 7, v20
	v_and_b32_e32 v21, 0x7f, v21
	v_and_b32_e32 v20, 0x3f80, v20
	v_bitop3_b32 v20, v21, s22, v20 bitop3:0x36
	v_lshl_add_u32 v21, v23, 2, v110
	ds_write2_b32 v21, v20, v22 offset0:80 offset1:208
; template <int C> DI void rank_step(const unsigned key, const int, int& rank) {
;   const unsigned o = (unsigned)__builtin_amdgcn_readlane((int)key, C);
;   rank += (o > key) ? 1 : 0;
; }
; DI void phase_peer_out(const Params& p, char* lds) {
;     ...
;     for (int hq = 0; hq < 8; ++hq) {
;       const float val = hval[hq];
;       const unsigned vb32 = __float_as_uint(val);
;       const unsigned ukey = cval ? (((vb32 ^ ((vb32 >> 31) ? 0xFFFFFFFFu : 0x80000000u)) & 0xFFFFFF00u) | (unsigned)(255 - flat)) : 0u;
;       int rank = 0;
;       rank_steps10<0>(ukey, flat, rank); rank_steps10<10>(ukey, flat, rank); rank_steps10<20>(ukey, flat, rank); rank_steps10<30>(ukey, flat, rank); rank_steps10<40>(ukey, flat, rank);
;       if (cval && rank < 16) { sidx[hq * 16 + rank] = hidx[hq]; sw[hq * 16 + rank] = val; }
.LBB0_1199:
	s_or_b64 exec, exec, s[12:13]
	v_and_b32_e32 v20, 0xffffff80, v18
	v_and_b32_e32 v21, 0xffffff80, v19
	v_add_f32_e32 v20, v20, v21
	v_cndmask_b32_e32 v21, v119, v20, vcc
	v_cmp_lt_i32_e64 s[12:13], -1, v21
	s_nop 1
	v_cndmask_b32_e64 v22, -1, v120, s[12:13]
	v_xor_b32_e32 v21, v22, v21
	v_and_or_b32 v21, v21, s21, v111
	v_cndmask_b32_e32 v21, 0, v21, vcc
	s_nop 0
	v_readlane_b32 s12, v21, 0
	s_nop 1
	v_cmp_gt_u32_e64 s[12:13], s12, v21
	s_nop 1
	v_cndmask_b32_e64 v22, 0, 1, s[12:13]
	v_readlane_b32 s12, v21, 1
	s_nop 1
	v_cmp_gt_u32_e64 s[12:13], s12, v21
	s_nop 1
	v_addc_co_u32_e64 v22, s[12:13], 0, v22, s[12:13]
	v_readlane_b32 s12, v21, 2
	s_nop 1
	v_cmp_gt_u32_e64 s[12:13], s12, v21
	s_nop 1
	v_cndmask_b32_e64 v23, 0, 1, s[12:13]
	v_readlane_b32 s12, v21, 3
	s_nop 1
	v_cmp_gt_u32_e64 s[12:13], s12, v21
	s_nop 1
	v_addc_co_u32_e64 v22, s[12:13], v22, v23, s[12:13]
	v_readlane_b32 s12, v21, 4
	s_nop 1
	v_cmp_gt_u32_e64 s[12:13], s12, v21
	s_nop 1
	v_cndmask_b32_e64 v23, 0, 1, s[12:13]
	v_readlane_b32 s12, v21, 5
	s_nop 1
	v_cmp_gt_u32_e64 s[12:13], s12, v21
	s_nop 1
	v_addc_co_u32_e64 v22, s[12:13], v22, v23, s[12:13]
	v_readlane_b32 s12, v21, 6
	s_nop 1
	v_cmp_gt_u32_e64 s[12:13], s12, v21
	s_nop 1
	v_cndmask_b32_e64 v23, 0, 1, s[12:13]
	v_readlane_b32 s12, v21, 7
	s_nop 1
	v_cmp_gt_u32_e64 s[12:13], s12, v21
	s_nop 1
	v_addc_co_u32_e64 v22, s[12:13], v22, v23, s[12:13]
	v_readlane_b32 s12, v21, 8
	s_nop 1
	v_cmp_gt_u32_e64 s[12:13], s12, v21
	s_nop 1
	v_cndmask_b32_e64 v23, 0, 1, s[12:13]
	v_readlane_b32 s12, v21, 9
	s_nop 1
	v_cmp_gt_u32_e64 s[12:13], s12, v21
	s_nop 1
	v_addc_co_u32_e64 v22, s[12:13], v22, v23, s[12:13]
	v_readlane_b32 s12, v21, 10
	s_nop 1
	v_cmp_gt_u32_e64 s[12:13], s12, v21
	s_nop 1
	v_cndmask_b32_e64 v23, 0, 1, s[12:13]
	v_readlane_b32 s12, v21, 11
	s_nop 1
	v_cmp_gt_u32_e64 s[12:13], s12, v21
	s_nop 1
	v_addc_co_u32_e64 v22, s[12:13], v22, v23, s[12:13]
	v_readlane_b32 s12, v21, 12
	s_nop 1
	v_cmp_gt_u32_e64 s[12:13], s12, v21
	s_nop 1
	v_cndmask_b32_e64 v23, 0, 1, s[12:13]
	v_readlane_b32 s12, v21, 13
	s_nop 1
	v_cmp_gt_u32_e64 s[12:13], s12, v21
	s_nop 1
	v_addc_co_u32_e64 v22, s[12:13], v22, v23, s[12:13]
	v_readlane_b32 s12, v21, 14
	s_nop 1
	v_cmp_gt_u32_e64 s[12:13], s12, v21
	s_nop 1
	v_cndmask_b32_e64 v23, 0, 1, s[12:13]
	v_readlane_b32 s12, v21, 15
	s_nop 1
	v_cmp_gt_u32_e64 s[12:13], s12, v21
	s_nop 1
	v_addc_co_u32_e64 v22, s[12:13], v22, v23, s[12:13]
	v_readlane_b32 s12, v21, 16
	s_nop 1
	v_cmp_gt_u32_e64 s[12:13], s12, v21
	s_nop 1
	v_cndmask_b32_e64 v23, 0, 1, s[12:13]
	v_readlane_b32 s12, v21, 17
	s_nop 1
	v_cmp_gt_u32_e64 s[12:13], s12, v21
	s_nop 1
	v_addc_co_u32_e64 v22, s[12:13], v22, v23, s[12:13]
	v_readlane_b32 s12, v21, 18
	s_nop 1
	v_cmp_gt_u32_e64 s[12:13], s12, v21
	s_nop 1
	v_cndmask_b32_e64 v23, 0, 1, s[12:13]
	v_readlane_b32 s12, v21, 19
	s_nop 1
	v_cmp_gt_u32_e64 s[12:13], s12, v21
	s_nop 1
	v_addc_co_u32_e64 v22, s[12:13], v22, v23, s[12:13]
	v_readlane_b32 s12, v21, 20
	s_nop 1
	v_cmp_gt_u32_e64 s[12:13], s12, v21
	s_nop 1
	v_cndmask_b32_e64 v23, 0, 1, s[12:13]
	v_readlane_b32 s12, v21, 21
	s_nop 1
	v_cmp_gt_u32_e64 s[12:13], s12, v21
	s_nop 1
	v_addc_co_u32_e64 v22, s[12:13], v22, v23, s[12:13]
	v_readlane_b32 s12, v21, 22
	s_nop 1
	v_cmp_gt_u32_e64 s[12:13], s12, v21
	s_nop 1
	v_cndmask_b32_e64 v23, 0, 1, s[12:13]
	v_readlane_b32 s12, v21, 23
	s_nop 1
	v_cmp_gt_u32_e64 s[12:13], s12, v21
	s_nop 1
	v_addc_co_u32_e64 v22, s[12:13], v22, v23, s[12:13]
	v_readlane_b32 s12, v21, 24
	s_nop 1
	v_cmp_gt_u32_e64 s[12:13], s12, v21
	s_nop 1
	v_cndmask_b32_e64 v23, 0, 1, s[12:13]
	v_readlane_b32 s12, v21, 25
	s_nop 1
	v_cmp_gt_u32_e64 s[12:13], s12, v21
	s_nop 1
	v_addc_co_u32_e64 v22, s[12:13], v22, v23, s[12:13]
	v_readlane_b32 s12, v21, 26
	s_nop 1
	v_cmp_gt_u32_e64 s[12:13], s12, v21
	s_nop 1
	v_cndmask_b32_e64 v23, 0, 1, s[12:13]
	v_readlane_b32 s12, v21, 27
	s_nop 1
	v_cmp_gt_u32_e64 s[12:13], s12, v21
	s_nop 1
	v_addc_co_u32_e64 v22, s[12:13], v22, v23, s[12:13]
	v_readlane_b32 s12, v21, 28
	s_nop 1
	v_cmp_gt_u32_e64 s[12:13], s12, v21
	s_nop 1
	v_cndmask_b32_e64 v23, 0, 1, s[12:13]
	v_readlane_b32 s12, v21, 29
	s_nop 1
	v_cmp_gt_u32_e64 s[12:13], s12, v21
	s_nop 1
	v_addc_co_u32_e64 v22, s[12:13], v22, v23, s[12:13]
	v_readlane_b32 s12, v21, 30
	s_nop 1
	v_cmp_gt_u32_e64 s[12:13], s12, v21
	s_nop 1
	v_cndmask_b32_e64 v23, 0, 1, s[12:13]
	v_readlane_b32 s12, v21, 31
	s_nop 1
	v_cmp_gt_u32_e64 s[12:13], s12, v21
	s_nop 1
	v_addc_co_u32_e64 v22, s[12:13], v22, v23, s[12:13]
	v_readlane_b32 s12, v21, 32
	s_nop 1
	v_cmp_gt_u32_e64 s[12:13], s12, v21
	s_nop 1
	v_cndmask_b32_e64 v23, 0, 1, s[12:13]
	v_readlane_b32 s12, v21, 33
	s_nop 1
	v_cmp_gt_u32_e64 s[12:13], s12, v21
	s_nop 1
	v_addc_co_u32_e64 v22, s[12:13], v22, v23, s[12:13]
	v_readlane_b32 s12, v21, 34
	s_nop 1
	v_cmp_gt_u32_e64 s[12:13], s12, v21
	s_nop 1
	v_cndmask_b32_e64 v23, 0, 1, s[12:13]
	v_readlane_b32 s12, v21, 35
	s_nop 1
	v_cmp_gt_u32_e64 s[12:13], s12, v21
	s_nop 1
	v_addc_co_u32_e64 v22, s[12:13], v22, v23, s[12:13]
	v_readlane_b32 s12, v21, 36
	s_nop 1
	v_cmp_gt_u32_e64 s[12:13], s12, v21
	s_nop 1
	v_cndmask_b32_e64 v23, 0, 1, s[12:13]
	v_readlane_b32 s12, v21, 37
	s_nop 1
	v_cmp_gt_u32_e64 s[12:13], s12, v21
	s_nop 1
	v_addc_co_u32_e64 v22, s[12:13], v22, v23, s[12:13]
	v_readlane_b32 s12, v21, 38
	s_nop 1
	v_cmp_gt_u32_e64 s[12:13], s12, v21
	s_nop 1
	v_cndmask_b32_e64 v23, 0, 1, s[12:13]
	v_readlane_b32 s12, v21, 39
	s_nop 1
	v_cmp_gt_u32_e64 s[12:13], s12, v21
	s_nop 1
	v_addc_co_u32_e64 v22, s[12:13], v22, v23, s[12:13]
	v_readlane_b32 s12, v21, 40
	s_nop 1
	v_cmp_gt_u32_e64 s[12:13], s12, v21
	s_nop 1
	v_cndmask_b32_e64 v23, 0, 1, s[12:13]
	v_readlane_b32 s12, v21, 41
	s_nop 1
	v_cmp_gt_u32_e64 s[12:13], s12, v21
	s_nop 1
	v_addc_co_u32_e64 v22, s[12:13], v22, v23, s[12:13]
	v_readlane_b32 s12, v21, 42
	s_nop 1
	v_cmp_gt_u32_e64 s[12:13], s12, v21
	s_nop 1
	v_cndmask_b32_e64 v23, 0, 1, s[12:13]
	v_readlane_b32 s12, v21, 43
	s_nop 1
	v_cmp_gt_u32_e64 s[12:13], s12, v21
	s_nop 1
	v_addc_co_u32_e64 v22, s[12:13], v22, v23, s[12:13]
	v_readlane_b32 s12, v21, 44
	s_nop 1
	v_cmp_gt_u32_e64 s[12:13], s12, v21
	s_nop 1
	v_cndmask_b32_e64 v23, 0, 1, s[12:13]
	v_readlane_b32 s12, v21, 45
	s_nop 1
	v_cmp_gt_u32_e64 s[12:13], s12, v21
	s_nop 1
	v_addc_co_u32_e64 v22, s[12:13], v22, v23, s[12:13]
	v_readlane_b32 s12, v21, 46
	s_nop 1
	v_cmp_gt_u32_e64 s[12:13], s12, v21
	s_nop 1
	v_cndmask_b32_e64 v23, 0, 1, s[12:13]
	v_readlane_b32 s12, v21, 47
	s_nop 1
	v_cmp_gt_u32_e64 s[12:13], s12, v21
	s_nop 1
	v_addc_co_u32_e64 v22, s[12:13], v22, v23, s[12:13]
	v_readlane_b32 s12, v21, 48
	s_nop 1
	v_cmp_gt_u32_e64 s[12:13], s12, v21
	s_nop 1
	v_cndmask_b32_e64 v23, 0, 1, s[12:13]
	v_readlane_b32 s12, v21, 49
	s_nop 1
	v_cmp_gt_u32_e64 s[12:13], s12, v21
	s_nop 1
	v_addc_co_u32_e64 v21, s[12:13], v22, v23, s[12:13]
	v_cmp_gt_u32_e64 s[12:13], 16, v21
	s_and_b64 s[16:17], vcc, s[12:13]
	s_and_saveexec_b64 s[12:13], s[16:17]
	s_cbranch_execz .LBB0_1201
; template <int C> DI void rank_step(const unsigned key, const int, int& rank) {
;   const unsigned o = (unsigned)__builtin_amdgcn_readlane((int)key, C);
;   rank += (o > key) ? 1 : 0;
; }
; DI void phase_peer_out(const Params& p, char* lds) {
;     ...
;     for (int hq = 0; hq < 8; ++hq) {
;       const float val = hval[hq];
;       const unsigned vb32 = __float_as_uint(val);
;       const unsigned ukey = cval ? (((vb32 ^ ((vb32 >> 31) ? 0xFFFFFFFFu : 0x80000000u)) & 0xFFFFFF00u) | (unsigned)(255 - flat)) : 0u;
;       int rank = 0;
;       rank_steps10<0>(ukey, flat, rank); rank_steps10<10>(ukey, flat, rank); rank_steps10<20>(ukey, flat, rank); rank_steps10<30>(ukey, flat, rank); rank_steps10<40>(ukey, flat, rank);
;       if (cval && rank < 16) { sidx[hq * 16 + rank] = hidx[hq]; sw[hq * 16 + rank] = val; }
	v_lshlrev_b32_e32 v18, 7, v18
	v_and_b32_e32 v19, 0x7f, v19
	v_and_b32_e32 v18, 0x3f80, v18
	v_bitop3_b32 v18, v19, s22, v18 bitop3:0x36
	v_lshl_add_u32 v19, v21, 2, v110
	ds_write2_b32 v19, v18, v20 offset0:96 offset1:224
.LBB0_1201:
	s_or_b64 exec, exec, s[12:13]
	v_and_b32_e32 v18, 0xffffff80, v16
	v_and_b32_e32 v19, 0xffffff80, v17
	v_add_f32_e32 v18, v18, v19
	v_cndmask_b32_e32 v19, v119, v18, vcc
	v_cmp_lt_i32_e64 s[12:13], -1, v19
	s_nop 1
	v_cndmask_b32_e64 v20, -1, v120, s[12:13]
	v_xor_b32_e32 v19, v20, v19
	v_and_or_b32 v19, v19, s21, v111
	v_cndmask_b32_e32 v19, 0, v19, vcc
	s_nop 0
	v_readlane_b32 s12, v19, 0
	s_nop 1
	v_cmp_gt_u32_e64 s[12:13], s12, v19
	s_nop 1
	v_cndmask_b32_e64 v20, 0, 1, s[12:13]
	v_readlane_b32 s12, v19, 1
	s_nop 1
	v_cmp_gt_u32_e64 s[12:13], s12, v19
	s_nop 1
	v_addc_co_u32_e64 v20, s[12:13], 0, v20, s[12:13]
	v_readlane_b32 s12, v19, 2
	s_nop 1
	v_cmp_gt_u32_e64 s[12:13], s12, v19
	s_nop 1
	v_cndmask_b32_e64 v21, 0, 1, s[12:13]
	v_readlane_b32 s12, v19, 3
	s_nop 1
	v_cmp_gt_u32_e64 s[12:13], s12, v19
	s_nop 1
	v_addc_co_u32_e64 v20, s[12:13], v20, v21, s[12:13]
	v_readlane_b32 s12, v19, 4
	s_nop 1
	v_cmp_gt_u32_e64 s[12:13], s12, v19
	s_nop 1
	v_cndmask_b32_e64 v21, 0, 1, s[12:13]
	v_readlane_b32 s12, v19, 5
	s_nop 1
	v_cmp_gt_u32_e64 s[12:13], s12, v19
	s_nop 1
	v_addc_co_u32_e64 v20, s[12:13], v20, v21, s[12:13]
	v_readlane_b32 s12, v19, 6
	s_nop 1
	v_cmp_gt_u32_e64 s[12:13], s12, v19
	s_nop 1
	v_cndmask_b32_e64 v21, 0, 1, s[12:13]
	v_readlane_b32 s12, v19, 7
	s_nop 1
	v_cmp_gt_u32_e64 s[12:13], s12, v19
	s_nop 1
	v_addc_co_u32_e64 v20, s[12:13], v20, v21, s[12:13]
	v_readlane_b32 s12, v19, 8
	s_nop 1
	v_cmp_gt_u32_e64 s[12:13], s12, v19
	s_nop 1
	v_cndmask_b32_e64 v21, 0, 1, s[12:13]
	v_readlane_b32 s12, v19, 9
	s_nop 1
	v_cmp_gt_u32_e64 s[12:13], s12, v19
	s_nop 1
	v_addc_co_u32_e64 v20, s[12:13], v20, v21, s[12:13]
	v_readlane_b32 s12, v19, 10
	s_nop 1
	v_cmp_gt_u32_e64 s[12:13], s12, v19
	s_nop 1
	v_cndmask_b32_e64 v21, 0, 1, s[12:13]
	v_readlane_b32 s12, v19, 11
	s_nop 1
	v_cmp_gt_u32_e64 s[12:13], s12, v19
	s_nop 1
	v_addc_co_u32_e64 v20, s[12:13], v20, v21, s[12:13]
	v_readlane_b32 s12, v19, 12
	s_nop 1
	v_cmp_gt_u32_e64 s[12:13], s12, v19
	s_nop 1
	v_cndmask_b32_e64 v21, 0, 1, s[12:13]
	v_readlane_b32 s12, v19, 13
	s_nop 1
	v_cmp_gt_u32_e64 s[12:13], s12, v19
	s_nop 1
	v_addc_co_u32_e64 v20, s[12:13], v20, v21, s[12:13]
	v_readlane_b32 s12, v19, 14
	s_nop 1
	v_cmp_gt_u32_e64 s[12:13], s12, v19
	s_nop 1
	v_cndmask_b32_e64 v21, 0, 1, s[12:13]
	v_readlane_b32 s12, v19, 15
	s_nop 1
	v_cmp_gt_u32_e64 s[12:13], s12, v19
	s_nop 1
	v_addc_co_u32_e64 v20, s[12:13], v20, v21, s[12:13]
	v_readlane_b32 s12, v19, 16
	s_nop 1
	v_cmp_gt_u32_e64 s[12:13], s12, v19
	s_nop 1
	v_cndmask_b32_e64 v21, 0, 1, s[12:13]
	v_readlane_b32 s12, v19, 17
	s_nop 1
	v_cmp_gt_u32_e64 s[12:13], s12, v19
	s_nop 1
	v_addc_co_u32_e64 v20, s[12:13], v20, v21, s[12:13]
	v_readlane_b32 s12, v19, 18
	s_nop 1
	v_cmp_gt_u32_e64 s[12:13], s12, v19
	s_nop 1
	v_cndmask_b32_e64 v21, 0, 1, s[12:13]
	v_readlane_b32 s12, v19, 19
	s_nop 1
	v_cmp_gt_u32_e64 s[12:13], s12, v19
	s_nop 1
	v_addc_co_u32_e64 v20, s[12:13], v20, v21, s[12:13]
	v_readlane_b32 s12, v19, 20
	s_nop 1
	v_cmp_gt_u32_e64 s[12:13], s12, v19
	s_nop 1
	v_cndmask_b32_e64 v21, 0, 1, s[12:13]
	v_readlane_b32 s12, v19, 21
	s_nop 1
	v_cmp_gt_u32_e64 s[12:13], s12, v19
	s_nop 1
	v_addc_co_u32_e64 v20, s[12:13], v20, v21, s[12:13]
	v_readlane_b32 s12, v19, 22
	s_nop 1
	v_cmp_gt_u32_e64 s[12:13], s12, v19
	s_nop 1
	v_cndmask_b32_e64 v21, 0, 1, s[12:13]
	v_readlane_b32 s12, v19, 23
	s_nop 1
	v_cmp_gt_u32_e64 s[12:13], s12, v19
	s_nop 1
	v_addc_co_u32_e64 v20, s[12:13], v20, v21, s[12:13]
	v_readlane_b32 s12, v19, 24
; template <int C> DI void rank_step(const unsigned key, const int, int& rank) {
;   const unsigned o = (unsigned)__builtin_amdgcn_readlane((int)key, C);
;   rank += (o > key) ? 1 : 0;
; }
; DI void phase_peer_out(const Params& p, char* lds) {
;     ...
;     for (int hq = 0; hq < 8; ++hq) {
;       const float val = hval[hq];
;       const unsigned vb32 = __float_as_uint(val);
;       const unsigned ukey = cval ? (((vb32 ^ ((vb32 >> 31) ? 0xFFFFFFFFu : 0x80000000u)) & 0xFFFFFF00u) | (unsigned)(255 - flat)) : 0u;
;       int rank = 0;
;       rank_steps10<0>(ukey, flat, rank); rank_steps10<10>(ukey, flat, rank); rank_steps10<20>(ukey, flat, rank); rank_steps10<30>(ukey, flat, rank); rank_steps10<40>(ukey, flat, rank);
;       if (cval && rank < 16) { sidx[hq * 16 + rank] = hidx[hq]; sw[hq * 16 + rank] = val; }
	s_nop 1
	v_cmp_gt_u32_e64 s[12:13], s12, v19
	s_nop 1
	v_cndmask_b32_e64 v21, 0, 1, s[12:13]
	v_readlane_b32 s12, v19, 25
	s_nop 1
	v_cmp_gt_u32_e64 s[12:13], s12, v19
	s_nop 1
	v_addc_co_u32_e64 v20, s[12:13], v20, v21, s[12:13]
	v_readlane_b32 s12, v19, 26
	s_nop 1
	v_cmp_gt_u32_e64 s[12:13], s12, v19
	s_nop 1
	v_cndmask_b32_e64 v21, 0, 1, s[12:13]
	v_readlane_b32 s12, v19, 27
	s_nop 1
	v_cmp_gt_u32_e64 s[12:13], s12, v19
	s_nop 1
	v_addc_co_u32_e64 v20, s[12:13], v20, v21, s[12:13]
	v_readlane_b32 s12, v19, 28
	s_nop 1
	v_cmp_gt_u32_e64 s[12:13], s12, v19
	s_nop 1
	v_cndmask_b32_e64 v21, 0, 1, s[12:13]
	v_readlane_b32 s12, v19, 29
	s_nop 1
	v_cmp_gt_u32_e64 s[12:13], s12, v19
	s_nop 1
	v_addc_co_u32_e64 v20, s[12:13], v20, v21, s[12:13]
	v_readlane_b32 s12, v19, 30
	s_nop 1
	v_cmp_gt_u32_e64 s[12:13], s12, v19
	s_nop 1
	v_cndmask_b32_e64 v21, 0, 1, s[12:13]
	v_readlane_b32 s12, v19, 31
	s_nop 1
	v_cmp_gt_u32_e64 s[12:13], s12, v19
	s_nop 1
	v_addc_co_u32_e64 v20, s[12:13], v20, v21, s[12:13]
	v_readlane_b32 s12, v19, 32
	s_nop 1
	v_cmp_gt_u32_e64 s[12:13], s12, v19
	s_nop 1
	v_cndmask_b32_e64 v21, 0, 1, s[12:13]
	v_readlane_b32 s12, v19, 33
	s_nop 1
	v_cmp_gt_u32_e64 s[12:13], s12, v19
	s_nop 1
	v_addc_co_u32_e64 v20, s[12:13], v20, v21, s[12:13]
	v_readlane_b32 s12, v19, 34
	s_nop 1
	v_cmp_gt_u32_e64 s[12:13], s12, v19
	s_nop 1
	v_cndmask_b32_e64 v21, 0, 1, s[12:13]
	v_readlane_b32 s12, v19, 35
	s_nop 1
	v_cmp_gt_u32_e64 s[12:13], s12, v19
	s_nop 1
	v_addc_co_u32_e64 v20, s[12:13], v20, v21, s[12:13]
	v_readlane_b32 s12, v19, 36
	s_nop 1
	v_cmp_gt_u32_e64 s[12:13], s12, v19
	s_nop 1
	v_cndmask_b32_e64 v21, 0, 1, s[12:13]
	v_readlane_b32 s12, v19, 37
	s_nop 1
	v_cmp_gt_u32_e64 s[12:13], s12, v19
	s_nop 1
	v_addc_co_u32_e64 v20, s[12:13], v20, v21, s[12:13]
	v_readlane_b32 s12, v19, 38
	s_nop 1
	v_cmp_gt_u32_e64 s[12:13], s12, v19
	s_nop 1
	v_cndmask_b32_e64 v21, 0, 1, s[12:13]
	v_readlane_b32 s12, v19, 39
	s_nop 1
	v_cmp_gt_u32_e64 s[12:13], s12, v19
	s_nop 1
	v_addc_co_u32_e64 v20, s[12:13], v20, v21, s[12:13]
	v_readlane_b32 s12, v19, 40
	s_nop 1
	v_cmp_gt_u32_e64 s[12:13], s12, v19
	s_nop 1
	v_cndmask_b32_e64 v21, 0, 1, s[12:13]
	v_readlane_b32 s12, v19, 41
	s_nop 1
	v_cmp_gt_u32_e64 s[12:13], s12, v19
	s_nop 1
	v_addc_co_u32_e64 v20, s[12:13], v20, v21, s[12:13]
	v_readlane_b32 s12, v19, 42
	s_nop 1
	v_cmp_gt_u32_e64 s[12:13], s12, v19
	s_nop 1
	v_cndmask_b32_e64 v21, 0, 1, s[12:13]
	v_readlane_b32 s12, v19, 43
	s_nop 1
	v_cmp_gt_u32_e64 s[12:13], s12, v19
	s_nop 1
	v_addc_co_u32_e64 v20, s[12:13], v20, v21, s[12:13]
	v_readlane_b32 s12, v19, 44
	s_nop 1
	v_cmp_gt_u32_e64 s[12:13], s12, v19
	s_nop 1
	v_cndmask_b32_e64 v21, 0, 1, s[12:13]
	v_readlane_b32 s12, v19, 45
	s_nop 1
	v_cmp_gt_u32_e64 s[12:13], s12, v19
	s_nop 1
	v_addc_co_u32_e64 v20, s[12:13], v20, v21, s[12:13]
	v_readlane_b32 s12, v19, 46
	s_nop 1
	v_cmp_gt_u32_e64 s[12:13], s12, v19
	s_nop 1
	v_cndmask_b32_e64 v21, 0, 1, s[12:13]
	v_readlane_b32 s12, v19, 47
	s_nop 1
	v_cmp_gt_u32_e64 s[12:13], s12, v19
	s_nop 1
	v_addc_co_u32_e64 v20, s[12:13], v20, v21, s[12:13]
	v_readlane_b32 s12, v19, 48
	s_nop 1
	v_cmp_gt_u32_e64 s[12:13], s12, v19
	s_nop 1
	v_cndmask_b32_e64 v21, 0, 1, s[12:13]
	v_readlane_b32 s12, v19, 49
	s_nop 1
	v_cmp_gt_u32_e64 s[12:13], s12, v19
	s_nop 1
	v_addc_co_u32_e64 v19, s[12:13], v20, v21, s[12:13]
	v_cmp_gt_u32_e64 s[12:13], 16, v19
	s_and_b64 s[16:17], vcc, s[12:13]
	s_and_saveexec_b64 s[12:13], s[16:17]
	s_cbranch_execz .LBB0_1203
	v_lshlrev_b32_e32 v16, 7, v16
	v_and_b32_e32 v17, 0x7f, v17
	v_and_b32_e32 v16, 0x3f80, v16
	v_bitop3_b32 v16, v17, s22, v16 bitop3:0x36
	v_lshl_add_u32 v17, v19, 2, v110
	ds_write2_b32 v17, v16, v18 offset0:112 offset1:240
